# attention epilogues: gate loads of adjacent column groups fetched as one global_load_dwordx4 per lane and un-crossed with v_permlane32_swap (10/9/5/5 load instructions instead of 16/16/8/8)
# speedup vs baseline: 1.0339x; 1.0026x over previous
; DI float bf2f(unsigned b) { return __uint_as_float(b << 16); }
; template <int DQK, int W1, int DV, int VW, int MODE> ...
;     ...
;   const float inv = __builtin_amdgcn_rcpf(xhalf_sum(l));
;   u32x2 ggv[NCB * 4];
; #pragma unroll
;   for (int cb = 0; cb < NCB; ++cb)
; #pragma unroll
;     for (int g = 0; g < 4; ++g) ggv[cb * 4 + g] = *(const u32x2*)(grow + 32 * cb + 8 * g + 4 * hi);
;   __builtin_amdgcn_sched_barrier(0);
; #pragma unroll
;   for (int cb = 0; cb < NCB; ++cb)
; #pragma unroll
;     for (int g = 0; g < 4; ++g) {
;       const int dv = 32 * cb + 8 * g + 4 * hi;
;       const u32x2 gg = ggv[cb * 4 + g];
;       float gv[4] = {bf2f(gg[0] & 0xffffu), bf2f(gg[0] >> 16), bf2f(gg[1] & 0xffffu), bf2f(gg[1] >> 16)};
;       float ov[4];
; #pragma unroll
;       for (int j = 0; j < 4; ++j) {
;         const float sg = gv[j] * __builtin_amdgcn_rcpf(1.f + __builtin_amdgcn_exp2f(-LOG2E * gv[j]));
;         ov[j] = o[cb][4 * g + j] * inv * sg;
;       }
;       *(unsigned*)((unsigned char*)yrow + dv) = pk4_fp8(ov[0] * Y_SCALE, ov[1] * Y_SCALE, ov[2] * Y_SCALE, ov[3] * Y_SCALE);
;       __builtin_amdgcn_sched_barrier(0);
;     }
.LBB0_1238:
	s_lshl_b32 s0, s27, 7
	v_lshlrev_b64 v[2:3], 13, v[184:185]
	s_ashr_i32 s1, s0, 31
	v_lshl_add_u64 v[2:3], s[6:7], 0, v[2:3]
	v_lshl_add_u64 v[2:3], s[0:1], 1, v[2:3]
	v_lshlrev_b32_e32 v0, 1, v188
	v_lshl_add_u64 v[2:3], v[2:3], 0, v[0:1]
	v_bfe_i32 v211, v179, 5, 1
	v_mul_i32_i24_e32 v210, 24, v211
	v_lshl_add_u64 v[208:209], v[2:3], 0, v[210:211]
	global_load_dwordx2 v[4:5], v[2:3], off offset:2048
	global_load_dwordx4 v[94:97], v[208:209], off offset:2080
	global_load_dwordx4 v[90:93], v[208:209], off offset:2112
	global_load_dwordx4 v[86:89], v[208:209], off offset:2144
	global_load_dwordx4 v[82:85], v[208:209], off offset:2176
	global_load_dwordx2 v[80:81], v[2:3], off offset:2192
	global_load_dwordx4 v[12:15], v[208:209], off offset:2224
	global_load_dwordx4 v[8:11], v[208:209], off offset:2256
	global_load_dwordx2 v[6:7], v[2:3], off offset:2272
	s_nop 0
	global_load_dwordx2 v[2:3], v[2:3], off offset:2288
	v_mov_b32_e32 v0, v236
	s_nop 1
	v_permlane32_swap_b32_e32 v236, v0
	v_readlane_b32 s28, v254, 27
	v_add_f32_e32 v0, v236, v0
	v_lshl_add_u64 v[98:99], s[82:83], 0, v[182:183]
	v_readlane_b32 s29, v254, 28
	v_rcp_f32_e32 v0, v0
	v_lshl_add_u64 v[98:99], v[98:99], 0, s[0:1]
	v_mov_b32_e32 v189, v1
	s_waitcnt vmcnt(9)
	v_lshlrev_b32_e32 v100, 16, v4
	v_mul_f32_e32 v102, 0xbfb8aa3b, v100
	v_exp_f32_e32 v102, v102
	v_and_b32_e32 v4, 0xffff0000, v4
	v_mul_f32_e32 v64, v64, v0
	v_lshlrev_b32_e32 v101, 16, v5
	v_add_f32_e32 v102, 1.0, v102
	v_rcp_f32_e32 v102, v102
	v_mul_f32_e32 v65, v65, v0
	v_and_b32_e32 v5, 0xffff0000, v5
	v_mul_f32_e32 v66, v66, v0
	v_mul_f32_e32 v100, v102, v100
	v_mul_f32_e32 v64, v64, v100
	v_mul_f32_e32 v100, 0xbfb8aa3b, v4
	v_exp_f32_e32 v100, v100
	v_mul_f32_e32 v64, 0x41800000, v64
	v_med3_f32 v64, v64, s93, v223
	v_add_f32_e32 v100, 1.0, v100
	v_rcp_f32_e32 v100, v100
	s_nop 0
	v_mul_f32_e32 v4, v100, v4
	v_mul_f32_e32 v4, v65, v4
	v_mul_f32_e32 v65, 0xbfb8aa3b, v101
	v_exp_f32_e32 v65, v65
	v_mul_f32_e32 v4, 0x41800000, v4
	v_med3_f32 v4, v4, s93, v223
	v_add_f32_e32 v65, 1.0, v65
	v_rcp_f32_e32 v65, v65
	s_nop 0
	v_mul_f32_e32 v65, v65, v101
	v_mul_f32_e32 v65, v66, v65
	v_mul_f32_e32 v66, 0xbfb8aa3b, v5
	v_exp_f32_e32 v66, v66
	v_mul_f32_e32 v65, 0x41800000, v65
	v_add_f32_e32 v66, 1.0, v66
	v_rcp_f32_e32 v66, v66
	s_nop 0
	v_mul_f32_e32 v5, v66, v5
	v_mul_f32_e32 v66, v67, v0
	v_mul_f32_e32 v5, v66, v5
	v_mov_b32_e32 v212, v1
	v_cvt_pk_fp8_f32 v212, v64, v4
	v_mul_f32_e32 v5, 0x41800000, v5
	v_med3_f32 v4, v65, s93, v223
	v_med3_f32 v5, v5, s93, v223
	v_cvt_pk_fp8_f32 v212, v4, v5 op_sel:[0,0,1]
	v_lshl_add_u64 v[4:5], v[98:99], 0, v[188:189]
	s_waitcnt vmcnt(8)
	v_permlane32_swap_b32_e32 v94, v96
	v_permlane32_swap_b32_e32 v95, v97
	v_lshlrev_b32_e32 v64, 16, v96
	v_and_b32_e32 v65, 0xffff0000, v96
	v_mul_f32_e32 v96, 0xbfb8aa3b, v64
	v_exp_f32_e32 v96, v96
	v_mul_f32_e32 v68, v68, v0
	v_lshlrev_b32_e32 v66, 16, v97
	v_and_b32_e32 v67, 0xffff0000, v97
	v_add_f32_e32 v96, 1.0, v96
	v_rcp_f32_e32 v96, v96
	s_nop 0
	v_mul_f32_e32 v64, v96, v64
	v_mul_f32_e32 v64, v68, v64
	v_mul_f32_e32 v68, 0xbfb8aa3b, v65
	v_exp_f32_e32 v68, v68
	v_mul_f32_e32 v64, 0x41800000, v64
	v_med3_f32 v64, v64, s93, v223
	v_add_f32_e32 v68, 1.0, v68
	v_rcp_f32_e32 v68, v68
	s_nop 0
	v_mul_f32_e32 v65, v68, v65
	v_mul_f32_e32 v68, v69, v0
	v_mul_f32_e32 v65, v68, v65
	v_mul_f32_e32 v68, 0xbfb8aa3b, v66
	v_exp_f32_e32 v68, v68
	v_mul_f32_e32 v65, 0x41800000, v65
	v_med3_f32 v65, v65, s93, v223
	v_add_f32_e32 v68, 1.0, v68
	v_rcp_f32_e32 v68, v68
	s_nop 0
	v_mul_f32_e32 v66, v68, v66
	v_mul_f32_e32 v68, v70, v0
	v_mul_f32_e32 v66, v68, v66
	v_mul_f32_e32 v68, 0xbfb8aa3b, v67
	v_exp_f32_e32 v68, v68
	v_mul_f32_e32 v66, 0x41800000, v66
	v_add_f32_e32 v68, 1.0, v68
	v_rcp_f32_e32 v68, v68
	s_nop 0
	v_mul_f32_e32 v67, v68, v67
	v_mul_f32_e32 v68, v71, v0
	v_mul_f32_e32 v67, v68, v67
	v_mov_b32_e32 v214, v1
	v_cvt_pk_fp8_f32 v214, v64, v65
	v_mul_f32_e32 v67, 0x41800000, v67
	v_med3_f32 v64, v66, s93, v223
	v_med3_f32 v65, v67, s93, v223
	v_cvt_pk_fp8_f32 v214, v64, v65 op_sel:[0,0,1]
	s_waitcnt vmcnt(8)
	v_lshlrev_b32_e32 v64, 16, v94
	v_mul_f32_e32 v68, 0xbfb8aa3b, v64
	v_exp_f32_e32 v68, v68
	v_and_b32_e32 v65, 0xffff0000, v94
	v_lshlrev_b32_e32 v66, 16, v95
	v_and_b32_e32 v67, 0xffff0000, v95
	v_add_f32_e32 v68, 1.0, v68
	v_rcp_f32_e32 v68, v68
	s_nop 0
	v_mul_f32_e32 v64, v68, v64
	v_mul_f32_e32 v68, v72, v0
	v_mul_f32_e32 v64, v68, v64
	v_mul_f32_e32 v68, 0xbfb8aa3b, v65
	v_exp_f32_e32 v68, v68
	v_mul_f32_e32 v64, 0x41800000, v64
	v_med3_f32 v64, v64, s93, v223
	v_add_f32_e32 v68, 1.0, v68
	v_rcp_f32_e32 v68, v68
	s_nop 0
	v_mul_f32_e32 v65, v68, v65
	v_mul_f32_e32 v68, v73, v0
	v_mul_f32_e32 v65, v68, v65
	v_mul_f32_e32 v68, 0xbfb8aa3b, v66
	v_exp_f32_e32 v68, v68
	v_mul_f32_e32 v65, 0x41800000, v65
	v_med3_f32 v65, v65, s93, v223
	v_add_f32_e32 v68, 1.0, v68
	v_rcp_f32_e32 v68, v68
	s_nop 0
	v_mul_f32_e32 v66, v68, v66
	v_mul_f32_e32 v68, v74, v0
	v_mul_f32_e32 v66, v68, v66
	v_mul_f32_e32 v68, 0xbfb8aa3b, v67
	v_exp_f32_e32 v68, v68
	v_mul_f32_e32 v66, 0x41800000, v66
	v_add_f32_e32 v68, 1.0, v68
	v_rcp_f32_e32 v68, v68
	s_nop 0
	v_mul_f32_e32 v67, v68, v67
	v_mul_f32_e32 v68, v75, v0
	v_mul_f32_e32 v67, v68, v67
	v_mov_b32_e32 v213, v1
	v_cvt_pk_fp8_f32 v213, v64, v65
	v_mul_f32_e32 v67, 0x41800000, v67
	v_med3_f32 v64, v66, s93, v223
	v_med3_f32 v65, v67, s93, v223
	v_cvt_pk_fp8_f32 v213, v64, v65 op_sel:[0,0,1]
	s_waitcnt vmcnt(7)
; DI float bf2f(unsigned b) { return __uint_as_float(b << 16); }
; template <int DQK, int W1, int DV, int VW, int MODE> ...
;     ...
; #pragma unroll
;   for (int cb = 0; cb < NCB; ++cb)
; #pragma unroll
;     for (int g = 0; g < 4; ++g) {
;       const int dv = 32 * cb + 8 * g + 4 * hi;
;       const u32x2 gg = ggv[cb * 4 + g];
;       float gv[4] = {bf2f(gg[0] & 0xffffu), bf2f(gg[0] >> 16), bf2f(gg[1] & 0xffffu), bf2f(gg[1] >> 16)};
;       float ov[4];
; #pragma unroll
;       for (int j = 0; j < 4; ++j) {
;         const float sg = gv[j] * __builtin_amdgcn_rcpf(1.f + __builtin_amdgcn_exp2f(-LOG2E * gv[j]));
;         ov[j] = o[cb][4 * g + j] * inv * sg;
;       }
;       *(unsigned*)((unsigned char*)yrow + dv) = pk4_fp8(ov[0] * Y_SCALE, ov[1] * Y_SCALE, ov[2] * Y_SCALE, ov[3] * Y_SCALE);
;       __builtin_amdgcn_sched_barrier(0);
;     }
	v_permlane32_swap_b32_e32 v90, v92
	v_permlane32_swap_b32_e32 v91, v93
	v_lshlrev_b32_e32 v64, 16, v92
	v_mul_f32_e32 v68, 0xbfb8aa3b, v64
	v_exp_f32_e32 v68, v68
	v_and_b32_e32 v65, 0xffff0000, v92
	v_lshlrev_b32_e32 v66, 16, v93
	v_and_b32_e32 v67, 0xffff0000, v93
	v_add_f32_e32 v68, 1.0, v68
	v_rcp_f32_e32 v68, v68
	s_nop 0
	v_mul_f32_e32 v64, v68, v64
	v_mul_f32_e32 v68, v76, v0
	v_mul_f32_e32 v64, v68, v64
	v_mul_f32_e32 v68, 0xbfb8aa3b, v65
	v_exp_f32_e32 v68, v68
	v_mul_f32_e32 v64, 0x41800000, v64
	v_med3_f32 v64, v64, s93, v223
	v_add_f32_e32 v68, 1.0, v68
	v_rcp_f32_e32 v68, v68
	s_nop 0
	v_mul_f32_e32 v65, v68, v65
	v_mul_f32_e32 v68, v77, v0
	v_mul_f32_e32 v65, v68, v65
	v_mul_f32_e32 v68, 0xbfb8aa3b, v66
	v_exp_f32_e32 v68, v68
	v_mul_f32_e32 v65, 0x41800000, v65
	v_med3_f32 v65, v65, s93, v223
	v_add_f32_e32 v68, 1.0, v68
	v_rcp_f32_e32 v68, v68
	s_nop 0
	v_mul_f32_e32 v66, v68, v66
	v_mul_f32_e32 v68, v78, v0
	v_mul_f32_e32 v66, v68, v66
	v_mul_f32_e32 v68, 0xbfb8aa3b, v67
	v_exp_f32_e32 v68, v68
	v_mul_f32_e32 v66, 0x41800000, v66
	v_add_f32_e32 v68, 1.0, v68
	v_rcp_f32_e32 v68, v68
	s_nop 0
	v_mul_f32_e32 v67, v68, v67
	v_mul_f32_e32 v68, v79, v0
	v_mul_f32_e32 v67, v68, v67
	v_mov_b32_e32 v215, v1
	v_cvt_pk_fp8_f32 v215, v64, v65
	v_mul_f32_e32 v67, 0x41800000, v67
	v_med3_f32 v64, v66, s93, v223
	v_med3_f32 v65, v67, s93, v223
	v_cvt_pk_fp8_f32 v215, v64, v65 op_sel:[0,0,1]
	v_and_b32_e32 v242, 32, v179
	v_lshrrev_b32_e32 v242, 3, v242
	v_lshl_add_u32 v242, v242, 1, v242
	v_mov_b32_e32 v243, 0
	v_lshl_add_u64 v[216:217], v[4:5], 0, v[242:243]
	s_nop 1
	v_permlane32_swap_b32_e32 v212, v213
	v_permlane32_swap_b32_e32 v214, v215
	global_store_dwordx4 v[216:217], v[212:215], off
	s_waitcnt vmcnt(8)
	v_lshlrev_b32_e32 v64, 16, v90
	v_mul_f32_e32 v68, 0xbfb8aa3b, v64
	v_exp_f32_e32 v68, v68
	v_and_b32_e32 v65, 0xffff0000, v90
	v_mul_f32_e32 v48, v48, v0
	v_lshlrev_b32_e32 v66, 16, v91
	v_add_f32_e32 v68, 1.0, v68
	v_rcp_f32_e32 v68, v68
	v_mul_f32_e32 v49, v49, v0
	v_and_b32_e32 v67, 0xffff0000, v91
	v_mul_f32_e32 v50, v50, v0
	v_mul_f32_e32 v64, v68, v64
	v_mul_f32_e32 v48, v48, v64
	v_mul_f32_e32 v64, 0xbfb8aa3b, v65
	v_exp_f32_e32 v64, v64
	v_mul_f32_e32 v51, v51, v0
	v_mul_f32_e32 v48, 0x41800000, v48
	v_med3_f32 v48, v48, s93, v223
	v_add_f32_e32 v64, 1.0, v64
	v_rcp_f32_e32 v64, v64
	s_nop 0
	v_mul_f32_e32 v64, v64, v65
	v_mul_f32_e32 v49, v49, v64
	v_mul_f32_e32 v64, 0xbfb8aa3b, v66
	v_exp_f32_e32 v64, v64
	v_mul_f32_e32 v49, 0x41800000, v49
	v_med3_f32 v49, v49, s93, v223
	v_add_f32_e32 v64, 1.0, v64
	v_rcp_f32_e32 v64, v64
	s_nop 0
	v_mul_f32_e32 v64, v64, v66
	v_mul_f32_e32 v50, v50, v64
	v_mul_f32_e32 v64, 0xbfb8aa3b, v67
	v_exp_f32_e32 v64, v64
	v_mul_f32_e32 v50, 0x41800000, v50
	v_add_f32_e32 v64, 1.0, v64
	v_rcp_f32_e32 v64, v64
	s_nop 0
	v_mul_f32_e32 v64, v64, v67
	v_mul_f32_e32 v51, v51, v64
	v_mov_b32_e32 v212, v1
	v_cvt_pk_fp8_f32 v212, v48, v49
	v_mul_f32_e32 v51, 0x41800000, v51
	v_med3_f32 v48, v50, s93, v223
	v_med3_f32 v49, v51, s93, v223
	v_cvt_pk_fp8_f32 v212, v48, v49 op_sel:[0,0,1]
	s_waitcnt vmcnt(7)
	v_permlane32_swap_b32_e32 v86, v88
	v_permlane32_swap_b32_e32 v87, v89
	v_lshlrev_b32_e32 v48, 16, v88
	v_mul_f32_e32 v64, 0xbfb8aa3b, v48
	v_exp_f32_e32 v64, v64
	v_and_b32_e32 v49, 0xffff0000, v88
	v_mul_f32_e32 v52, v52, v0
	v_lshlrev_b32_e32 v50, 16, v89
	v_add_f32_e32 v64, 1.0, v64
	v_rcp_f32_e32 v64, v64
	v_and_b32_e32 v51, 0xffff0000, v89
	v_mul_f32_e32 v48, v64, v48
	v_mul_f32_e32 v48, v52, v48
	v_mul_f32_e32 v52, 0xbfb8aa3b, v49
	v_exp_f32_e32 v52, v52
	v_mul_f32_e32 v48, 0x41800000, v48
	v_med3_f32 v48, v48, s93, v223
	v_add_f32_e32 v52, 1.0, v52
	v_rcp_f32_e32 v52, v52
	s_nop 0
	v_mul_f32_e32 v49, v52, v49
	v_mul_f32_e32 v52, v53, v0
	v_mul_f32_e32 v49, v52, v49
	v_mul_f32_e32 v52, 0xbfb8aa3b, v50
	v_exp_f32_e32 v52, v52
	v_mul_f32_e32 v49, 0x41800000, v49
	v_med3_f32 v49, v49, s93, v223
	v_add_f32_e32 v52, 1.0, v52
	v_rcp_f32_e32 v52, v52
	s_nop 0
	v_mul_f32_e32 v50, v52, v50
	v_mul_f32_e32 v52, v54, v0
	v_mul_f32_e32 v50, v52, v50
	v_mul_f32_e32 v52, 0xbfb8aa3b, v51
	v_exp_f32_e32 v52, v52
	v_mul_f32_e32 v50, 0x41800000, v50
	v_add_f32_e32 v52, 1.0, v52
	v_rcp_f32_e32 v52, v52
	s_nop 0
	v_mul_f32_e32 v51, v52, v51
	v_mul_f32_e32 v52, v55, v0
	v_mul_f32_e32 v51, v52, v51
	v_mov_b32_e32 v214, v1
	v_cvt_pk_fp8_f32 v214, v48, v49
	v_mul_f32_e32 v51, 0x41800000, v51
	v_med3_f32 v48, v50, s93, v223
	v_med3_f32 v49, v51, s93, v223
	v_cvt_pk_fp8_f32 v214, v48, v49 op_sel:[0,0,1]
	s_waitcnt vmcnt(7)
	v_lshlrev_b32_e32 v48, 16, v86
	v_mul_f32_e32 v52, 0xbfb8aa3b, v48
	v_exp_f32_e32 v52, v52
	v_and_b32_e32 v49, 0xffff0000, v86
	v_lshlrev_b32_e32 v50, 16, v87
	v_and_b32_e32 v51, 0xffff0000, v87
	v_add_f32_e32 v52, 1.0, v52
	v_rcp_f32_e32 v52, v52
	s_nop 0
	v_mul_f32_e32 v48, v52, v48
	v_mul_f32_e32 v52, v56, v0
	v_mul_f32_e32 v48, v52, v48
	v_mul_f32_e32 v52, 0xbfb8aa3b, v49
	v_exp_f32_e32 v52, v52
	v_mul_f32_e32 v48, 0x41800000, v48
	v_med3_f32 v48, v48, s93, v223
	v_add_f32_e32 v52, 1.0, v52
	v_rcp_f32_e32 v52, v52
	s_nop 0
	v_mul_f32_e32 v49, v52, v49
	v_mul_f32_e32 v52, v57, v0
	v_mul_f32_e32 v49, v52, v49
	v_mul_f32_e32 v52, 0xbfb8aa3b, v50
	v_exp_f32_e32 v52, v52
	v_mul_f32_e32 v49, 0x41800000, v49
	v_med3_f32 v49, v49, s93, v223
	v_add_f32_e32 v52, 1.0, v52
	v_rcp_f32_e32 v52, v52
	s_nop 0
	v_mul_f32_e32 v50, v52, v50
	v_mul_f32_e32 v52, v58, v0
	v_mul_f32_e32 v50, v52, v50
	v_mul_f32_e32 v52, 0xbfb8aa3b, v51
	v_exp_f32_e32 v52, v52
	v_mul_f32_e32 v50, 0x41800000, v50
	v_add_f32_e32 v52, 1.0, v52
	v_rcp_f32_e32 v52, v52
	s_nop 0
	v_mul_f32_e32 v51, v52, v51
	v_mul_f32_e32 v52, v59, v0
	v_mul_f32_e32 v51, v52, v51
	v_mov_b32_e32 v213, v1
	v_cvt_pk_fp8_f32 v213, v48, v49
	v_mul_f32_e32 v51, 0x41800000, v51
	v_med3_f32 v48, v50, s93, v223
	v_med3_f32 v49, v51, s93, v223
	v_cvt_pk_fp8_f32 v213, v48, v49 op_sel:[0,0,1]
	s_waitcnt vmcnt(6)
; DI float bf2f(unsigned b) { return __uint_as_float(b << 16); }
; template <int DQK, int W1, int DV, int VW, int MODE> ...
;     ...
; #pragma unroll
;   for (int cb = 0; cb < NCB; ++cb)
; #pragma unroll
;     for (int g = 0; g < 4; ++g) {
;       const int dv = 32 * cb + 8 * g + 4 * hi;
;       const u32x2 gg = ggv[cb * 4 + g];
;       float gv[4] = {bf2f(gg[0] & 0xffffu), bf2f(gg[0] >> 16), bf2f(gg[1] & 0xffffu), bf2f(gg[1] >> 16)};
;       float ov[4];
; #pragma unroll
;       for (int j = 0; j < 4; ++j) {
;         const float sg = gv[j] * __builtin_amdgcn_rcpf(1.f + __builtin_amdgcn_exp2f(-LOG2E * gv[j]));
;         ov[j] = o[cb][4 * g + j] * inv * sg;
;       }
;       *(unsigned*)((unsigned char*)yrow + dv) = pk4_fp8(ov[0] * Y_SCALE, ov[1] * Y_SCALE, ov[2] * Y_SCALE, ov[3] * Y_SCALE);
;       __builtin_amdgcn_sched_barrier(0);
;     }
	v_permlane32_swap_b32_e32 v82, v84
	v_permlane32_swap_b32_e32 v83, v85
	v_lshlrev_b32_e32 v48, 16, v84
	v_mul_f32_e32 v52, 0xbfb8aa3b, v48
	v_exp_f32_e32 v52, v52
	v_and_b32_e32 v49, 0xffff0000, v84
	v_lshlrev_b32_e32 v50, 16, v85
	v_and_b32_e32 v51, 0xffff0000, v85
	v_add_f32_e32 v52, 1.0, v52
	v_rcp_f32_e32 v52, v52
	s_nop 0
	v_mul_f32_e32 v48, v52, v48
	v_mul_f32_e32 v52, v60, v0
	v_mul_f32_e32 v48, v52, v48
	v_mul_f32_e32 v52, 0xbfb8aa3b, v49
	v_exp_f32_e32 v52, v52
	v_mul_f32_e32 v48, 0x41800000, v48
	v_med3_f32 v48, v48, s93, v223
	v_add_f32_e32 v52, 1.0, v52
	v_rcp_f32_e32 v52, v52
	s_nop 0
	v_mul_f32_e32 v49, v52, v49
	v_mul_f32_e32 v52, v61, v0
	v_mul_f32_e32 v49, v52, v49
	v_mul_f32_e32 v52, 0xbfb8aa3b, v50
	v_exp_f32_e32 v52, v52
	v_mul_f32_e32 v49, 0x41800000, v49
	v_med3_f32 v49, v49, s93, v223
	v_add_f32_e32 v52, 1.0, v52
	v_rcp_f32_e32 v52, v52
	s_nop 0
	v_mul_f32_e32 v50, v52, v50
	v_mul_f32_e32 v52, v62, v0
	v_mul_f32_e32 v50, v52, v50
	v_mul_f32_e32 v52, 0xbfb8aa3b, v51
	v_exp_f32_e32 v52, v52
	v_mul_f32_e32 v50, 0x41800000, v50
	v_add_f32_e32 v52, 1.0, v52
	v_rcp_f32_e32 v52, v52
	s_nop 0
	v_mul_f32_e32 v51, v52, v51
	v_mul_f32_e32 v52, v63, v0
	v_mul_f32_e32 v51, v52, v51
	v_mov_b32_e32 v215, v1
	v_cvt_pk_fp8_f32 v215, v48, v49
	v_mul_f32_e32 v51, 0x41800000, v51
	v_med3_f32 v48, v50, s93, v223
	v_med3_f32 v49, v51, s93, v223
	v_cvt_pk_fp8_f32 v215, v48, v49 op_sel:[0,0,1]
	s_nop 1
	v_permlane32_swap_b32_e32 v212, v213
	v_permlane32_swap_b32_e32 v214, v215
	global_store_dwordx4 v[216:217], v[212:215], off offset:32
	s_waitcnt vmcnt(7)
	v_lshlrev_b32_e32 v48, 16, v82
	v_mul_f32_e32 v52, 0xbfb8aa3b, v48
	v_exp_f32_e32 v52, v52
	v_and_b32_e32 v49, 0xffff0000, v82
	v_mul_f32_e32 v32, v32, v0
	v_lshlrev_b32_e32 v50, 16, v83
	v_add_f32_e32 v52, 1.0, v52
	v_rcp_f32_e32 v52, v52
	v_mul_f32_e32 v33, v33, v0
	v_and_b32_e32 v51, 0xffff0000, v83
	v_mul_f32_e32 v34, v34, v0
	v_mul_f32_e32 v48, v52, v48
	v_mul_f32_e32 v32, v32, v48
	v_mul_f32_e32 v48, 0xbfb8aa3b, v49
	v_exp_f32_e32 v48, v48
	v_mul_f32_e32 v35, v35, v0
	v_mul_f32_e32 v32, 0x41800000, v32
	v_med3_f32 v32, v32, s93, v223
	v_add_f32_e32 v48, 1.0, v48
	v_rcp_f32_e32 v48, v48
	s_nop 0
	v_mul_f32_e32 v48, v48, v49
	v_mul_f32_e32 v33, v33, v48
	v_mul_f32_e32 v48, 0xbfb8aa3b, v50
	v_exp_f32_e32 v48, v48
	v_mul_f32_e32 v33, 0x41800000, v33
	v_med3_f32 v33, v33, s93, v223
	v_add_f32_e32 v48, 1.0, v48
	v_rcp_f32_e32 v48, v48
	s_nop 0
	v_mul_f32_e32 v48, v48, v50
	v_mul_f32_e32 v34, v34, v48
	v_mul_f32_e32 v48, 0xbfb8aa3b, v51
	v_exp_f32_e32 v48, v48
	v_mul_f32_e32 v34, 0x41800000, v34
	v_add_f32_e32 v48, 1.0, v48
	v_rcp_f32_e32 v48, v48
	s_nop 0
	v_mul_f32_e32 v48, v48, v51
	v_mul_f32_e32 v35, v35, v48
	v_mov_b32_e32 v212, v1
	v_cvt_pk_fp8_f32 v212, v32, v33
	v_mul_f32_e32 v35, 0x41800000, v35
	v_med3_f32 v32, v34, s93, v223
	v_med3_f32 v33, v35, s93, v223
	v_cvt_pk_fp8_f32 v212, v32, v33 op_sel:[0,0,1]
	s_waitcnt vmcnt(6)
	v_lshlrev_b32_e32 v32, 16, v80
	v_mul_f32_e32 v48, 0xbfb8aa3b, v32
	v_exp_f32_e32 v48, v48
	v_and_b32_e32 v33, 0xffff0000, v80
	v_mul_f32_e32 v36, v36, v0
	v_lshlrev_b32_e32 v34, 16, v81
	v_add_f32_e32 v48, 1.0, v48
	v_rcp_f32_e32 v48, v48
	v_and_b32_e32 v35, 0xffff0000, v81
	v_mul_f32_e32 v32, v48, v32
	v_mul_f32_e32 v32, v36, v32
	v_mul_f32_e32 v36, 0xbfb8aa3b, v33
	v_exp_f32_e32 v36, v36
	v_mul_f32_e32 v32, 0x41800000, v32
	v_med3_f32 v32, v32, s93, v223
	v_add_f32_e32 v36, 1.0, v36
	v_rcp_f32_e32 v36, v36
	s_nop 0
	v_mul_f32_e32 v33, v36, v33
	v_mul_f32_e32 v36, v37, v0
	v_mul_f32_e32 v33, v36, v33
	v_mul_f32_e32 v36, 0xbfb8aa3b, v34
	v_exp_f32_e32 v36, v36
	v_mul_f32_e32 v33, 0x41800000, v33
	v_med3_f32 v33, v33, s93, v223
	v_add_f32_e32 v36, 1.0, v36
	v_rcp_f32_e32 v36, v36
	s_nop 0
	v_mul_f32_e32 v34, v36, v34
	v_mul_f32_e32 v36, v38, v0
	v_mul_f32_e32 v34, v36, v34
	v_mul_f32_e32 v36, 0xbfb8aa3b, v35
	v_exp_f32_e32 v36, v36
	v_mul_f32_e32 v34, 0x41800000, v34
	v_add_f32_e32 v36, 1.0, v36
	v_rcp_f32_e32 v36, v36
	s_nop 0
	v_mul_f32_e32 v35, v36, v35
	v_mul_f32_e32 v36, v39, v0
	v_mul_f32_e32 v35, v36, v35
	v_mov_b32_e32 v214, v1
	v_cvt_pk_fp8_f32 v214, v32, v33
	v_mul_f32_e32 v35, 0x41800000, v35
	v_med3_f32 v32, v34, s93, v223
	v_med3_f32 v33, v35, s93, v223
	v_cvt_pk_fp8_f32 v214, v32, v33 op_sel:[0,0,1]
	s_waitcnt vmcnt(5)
	v_permlane32_swap_b32_e32 v12, v14
	v_permlane32_swap_b32_e32 v13, v15
	v_lshlrev_b32_e32 v32, 16, v14
	v_mul_f32_e32 v34, 0xbfb8aa3b, v32
	v_exp_f32_e32 v34, v34
	v_and_b32_e32 v14, 0xffff0000, v14
	v_lshlrev_b32_e32 v33, 16, v15
	v_and_b32_e32 v15, 0xffff0000, v15
	v_add_f32_e32 v34, 1.0, v34
	v_rcp_f32_e32 v34, v34
	s_nop 0
	v_mul_f32_e32 v32, v34, v32
	v_mul_f32_e32 v34, v40, v0
	v_mul_f32_e32 v32, v34, v32
	v_mul_f32_e32 v34, 0xbfb8aa3b, v14
	v_exp_f32_e32 v34, v34
	v_mul_f32_e32 v32, 0x41800000, v32
	v_med3_f32 v32, v32, s93, v223
	v_add_f32_e32 v34, 1.0, v34
	v_rcp_f32_e32 v34, v34
	s_nop 0
	v_mul_f32_e32 v14, v34, v14
	v_mul_f32_e32 v34, v41, v0
	v_mul_f32_e32 v14, v34, v14
	v_mul_f32_e32 v34, 0xbfb8aa3b, v33
	v_exp_f32_e32 v34, v34
	v_mul_f32_e32 v14, 0x41800000, v14
	v_med3_f32 v14, v14, s93, v223
	v_add_f32_e32 v34, 1.0, v34
	v_rcp_f32_e32 v34, v34
	s_nop 0
	v_mul_f32_e32 v33, v34, v33
	v_mul_f32_e32 v34, v42, v0
	v_mul_f32_e32 v33, v34, v33
	v_mul_f32_e32 v34, 0xbfb8aa3b, v15
	v_exp_f32_e32 v34, v34
	v_mul_f32_e32 v33, 0x41800000, v33
	v_add_f32_e32 v34, 1.0, v34
	v_rcp_f32_e32 v34, v34
	s_nop 0
	v_mul_f32_e32 v15, v34, v15
	v_mul_f32_e32 v34, v43, v0
	v_mul_f32_e32 v15, v34, v15
	v_mov_b32_e32 v213, v1
	v_cvt_pk_fp8_f32 v213, v32, v14
	v_mul_f32_e32 v15, 0x41800000, v15
	v_med3_f32 v14, v33, s93, v223
	v_med3_f32 v15, v15, s93, v223
	v_cvt_pk_fp8_f32 v213, v14, v15 op_sel:[0,0,1]
	s_waitcnt vmcnt(5)
; DI float bf2f(unsigned b) { return __uint_as_float(b << 16); }
; template <int DQK, int W1, int DV, int VW, int MODE> ...
;     ...
; #pragma unroll
;   for (int cb = 0; cb < NCB; ++cb)
; #pragma unroll
;     for (int g = 0; g < 4; ++g) {
;       const int dv = 32 * cb + 8 * g + 4 * hi;
;       const u32x2 gg = ggv[cb * 4 + g];
;       float gv[4] = {bf2f(gg[0] & 0xffffu), bf2f(gg[0] >> 16), bf2f(gg[1] & 0xffffu), bf2f(gg[1] >> 16)};
;       float ov[4];
; #pragma unroll
;       for (int j = 0; j < 4; ++j) {
;         const float sg = gv[j] * __builtin_amdgcn_rcpf(1.f + __builtin_amdgcn_exp2f(-LOG2E * gv[j]));
;         ov[j] = o[cb][4 * g + j] * inv * sg;
;       }
;       *(unsigned*)((unsigned char*)yrow + dv) = pk4_fp8(ov[0] * Y_SCALE, ov[1] * Y_SCALE, ov[2] * Y_SCALE, ov[3] * Y_SCALE);
;       __builtin_amdgcn_sched_barrier(0);
;     }
	v_lshlrev_b32_e32 v14, 16, v12
	v_mul_f32_e32 v32, 0xbfb8aa3b, v14
	v_exp_f32_e32 v32, v32
	v_and_b32_e32 v12, 0xffff0000, v12
	v_lshlrev_b32_e32 v15, 16, v13
	v_and_b32_e32 v13, 0xffff0000, v13
	v_add_f32_e32 v32, 1.0, v32
	v_rcp_f32_e32 v32, v32
	s_nop 0
	v_mul_f32_e32 v14, v32, v14
	v_mul_f32_e32 v32, v44, v0
	v_mul_f32_e32 v14, v32, v14
	v_mul_f32_e32 v32, 0xbfb8aa3b, v12
	v_exp_f32_e32 v32, v32
	v_mul_f32_e32 v14, 0x41800000, v14
	v_med3_f32 v14, v14, s93, v223
	v_add_f32_e32 v32, 1.0, v32
	v_rcp_f32_e32 v32, v32
	s_nop 0
	v_mul_f32_e32 v12, v32, v12
	v_mul_f32_e32 v32, v45, v0
	v_mul_f32_e32 v12, v32, v12
	v_mul_f32_e32 v32, 0xbfb8aa3b, v15
	v_exp_f32_e32 v32, v32
	v_mul_f32_e32 v12, 0x41800000, v12
	v_med3_f32 v12, v12, s93, v223
	v_add_f32_e32 v32, 1.0, v32
	v_rcp_f32_e32 v32, v32
	s_nop 0
	v_mul_f32_e32 v15, v32, v15
	v_mul_f32_e32 v32, v46, v0
	v_mul_f32_e32 v15, v32, v15
	v_mul_f32_e32 v32, 0xbfb8aa3b, v13
	v_exp_f32_e32 v32, v32
	v_mul_f32_e32 v15, 0x41800000, v15
	v_add_f32_e32 v32, 1.0, v32
	v_rcp_f32_e32 v32, v32
	s_nop 0
	v_mul_f32_e32 v13, v32, v13
	v_mul_f32_e32 v32, v47, v0
	v_mul_f32_e32 v13, v32, v13
	v_mov_b32_e32 v215, v1
	v_cvt_pk_fp8_f32 v215, v14, v12
	v_mul_f32_e32 v13, 0x41800000, v13
	v_med3_f32 v12, v15, s93, v223
	v_med3_f32 v13, v13, s93, v223
	v_cvt_pk_fp8_f32 v215, v12, v13 op_sel:[0,0,1]
	s_nop 1
	v_permlane32_swap_b32_e32 v212, v213
	v_permlane32_swap_b32_e32 v214, v215
	global_store_dwordx4 v[216:217], v[212:215], off offset:64
	s_waitcnt vmcnt(5)
	v_permlane32_swap_b32_e32 v8, v10
	v_permlane32_swap_b32_e32 v9, v11
	v_lshlrev_b32_e32 v12, 16, v10
	v_mul_f32_e32 v14, 0xbfb8aa3b, v12
	v_exp_f32_e32 v14, v14
	v_and_b32_e32 v10, 0xffff0000, v10
	v_lshlrev_b32_e32 v13, 16, v11
	v_and_b32_e32 v11, 0xffff0000, v11
	v_add_f32_e32 v14, 1.0, v14
	v_rcp_f32_e32 v14, v14
	s_nop 0
	v_mul_f32_e32 v12, v14, v12
	v_mul_f32_e32 v14, v16, v0
	v_mul_f32_e32 v12, v14, v12
	v_mul_f32_e32 v14, 0xbfb8aa3b, v10
	v_exp_f32_e32 v14, v14
	v_mul_f32_e32 v12, 0x41800000, v12
	v_med3_f32 v12, v12, s93, v223
	v_add_f32_e32 v14, 1.0, v14
	v_rcp_f32_e32 v14, v14
	s_nop 0
	v_mul_f32_e32 v10, v14, v10
	v_mul_f32_e32 v14, v17, v0
	v_mul_f32_e32 v10, v14, v10
	v_mul_f32_e32 v14, 0xbfb8aa3b, v13
	v_exp_f32_e32 v14, v14
	v_mul_f32_e32 v10, 0x41800000, v10
	v_med3_f32 v10, v10, s93, v223
	v_add_f32_e32 v14, 1.0, v14
	v_rcp_f32_e32 v14, v14
	s_nop 0
	v_mul_f32_e32 v13, v14, v13
	v_mul_f32_e32 v14, v18, v0
	v_mul_f32_e32 v13, v14, v13
	v_mul_f32_e32 v14, 0xbfb8aa3b, v11
	v_exp_f32_e32 v14, v14
	v_mul_f32_e32 v13, 0x41800000, v13
	v_add_f32_e32 v14, 1.0, v14
	v_rcp_f32_e32 v14, v14
	s_nop 0
	v_mul_f32_e32 v11, v14, v11
	v_mul_f32_e32 v14, v19, v0
	v_mul_f32_e32 v11, v14, v11
	v_mov_b32_e32 v212, v1
	v_cvt_pk_fp8_f32 v212, v12, v10
	v_mul_f32_e32 v11, 0x41800000, v11
	v_med3_f32 v10, v13, s93, v223
	v_med3_f32 v11, v11, s93, v223
	v_cvt_pk_fp8_f32 v212, v10, v11 op_sel:[0,0,1]
	s_waitcnt vmcnt(5)
	v_lshlrev_b32_e32 v10, 16, v8
	v_mul_f32_e32 v12, 0xbfb8aa3b, v10
	v_exp_f32_e32 v12, v12
	v_and_b32_e32 v8, 0xffff0000, v8
	v_lshlrev_b32_e32 v11, 16, v9
	v_and_b32_e32 v9, 0xffff0000, v9
	v_add_f32_e32 v12, 1.0, v12
	v_rcp_f32_e32 v12, v12
	s_nop 0
	v_mul_f32_e32 v10, v12, v10
	v_mul_f32_e32 v12, v20, v0
	v_mul_f32_e32 v10, v12, v10
	v_mul_f32_e32 v12, 0xbfb8aa3b, v8
	v_exp_f32_e32 v12, v12
	v_mul_f32_e32 v10, 0x41800000, v10
	v_med3_f32 v10, v10, s93, v223
	v_add_f32_e32 v12, 1.0, v12
	v_rcp_f32_e32 v12, v12
	s_nop 0
	v_mul_f32_e32 v8, v12, v8
	v_mul_f32_e32 v12, v21, v0
	v_mul_f32_e32 v8, v12, v8
	v_mul_f32_e32 v12, 0xbfb8aa3b, v11
	v_exp_f32_e32 v12, v12
	v_mul_f32_e32 v8, 0x41800000, v8
	v_med3_f32 v8, v8, s93, v223
	v_add_f32_e32 v12, 1.0, v12
	v_rcp_f32_e32 v12, v12
	s_nop 0
	v_mul_f32_e32 v11, v12, v11
	v_mul_f32_e32 v12, v22, v0
	v_mul_f32_e32 v11, v12, v11
	v_mul_f32_e32 v12, 0xbfb8aa3b, v9
	v_exp_f32_e32 v12, v12
	v_mul_f32_e32 v11, 0x41800000, v11
	v_add_f32_e32 v12, 1.0, v12
	v_rcp_f32_e32 v12, v12
	s_nop 0
	v_mul_f32_e32 v9, v12, v9
	v_mul_f32_e32 v12, v23, v0
	v_mul_f32_e32 v9, v12, v9
	v_mov_b32_e32 v214, v1
	v_cvt_pk_fp8_f32 v214, v10, v8
	v_mul_f32_e32 v9, 0x41800000, v9
	v_med3_f32 v8, v11, s93, v223
	v_med3_f32 v9, v9, s93, v223
	v_cvt_pk_fp8_f32 v214, v8, v9 op_sel:[0,0,1]
	s_waitcnt vmcnt(4)
	v_lshlrev_b32_e32 v8, 16, v6
	v_mul_f32_e32 v10, 0xbfb8aa3b, v8
	v_exp_f32_e32 v10, v10
	v_and_b32_e32 v6, 0xffff0000, v6
	v_lshlrev_b32_e32 v9, 16, v7
	v_and_b32_e32 v7, 0xffff0000, v7
	v_add_f32_e32 v10, 1.0, v10
	v_rcp_f32_e32 v10, v10
	s_nop 0
	v_mul_f32_e32 v8, v10, v8
	v_mul_f32_e32 v10, v24, v0
	v_mul_f32_e32 v8, v10, v8
	v_mul_f32_e32 v10, 0xbfb8aa3b, v6
	v_exp_f32_e32 v10, v10
	v_mul_f32_e32 v8, 0x41800000, v8
	v_med3_f32 v8, v8, s93, v223
	v_add_f32_e32 v10, 1.0, v10
	v_rcp_f32_e32 v10, v10
	s_nop 0
	v_mul_f32_e32 v6, v10, v6
	v_mul_f32_e32 v10, v25, v0
	v_mul_f32_e32 v6, v10, v6
	v_mul_f32_e32 v10, 0xbfb8aa3b, v9
	v_exp_f32_e32 v10, v10
	v_mul_f32_e32 v6, 0x41800000, v6
	v_med3_f32 v6, v6, s93, v223
	v_add_f32_e32 v10, 1.0, v10
	v_rcp_f32_e32 v10, v10
	s_nop 0
	v_mul_f32_e32 v9, v10, v9
	v_mul_f32_e32 v10, v26, v0
	v_mul_f32_e32 v9, v10, v9
	v_mul_f32_e32 v10, 0xbfb8aa3b, v7
	v_exp_f32_e32 v10, v10
	v_mul_f32_e32 v9, 0x41800000, v9
	v_add_f32_e32 v10, 1.0, v10
	v_rcp_f32_e32 v10, v10
	s_nop 0
	v_mul_f32_e32 v7, v10, v7
	v_mul_f32_e32 v10, v27, v0
	v_mul_f32_e32 v7, v10, v7
	v_mov_b32_e32 v213, v1
	v_cvt_pk_fp8_f32 v213, v8, v6
	v_mul_f32_e32 v7, 0x41800000, v7
	v_med3_f32 v6, v9, s93, v223
	v_med3_f32 v7, v7, s93, v223
	v_cvt_pk_fp8_f32 v213, v6, v7 op_sel:[0,0,1]
	s_waitcnt vmcnt(3)
	v_lshlrev_b32_e32 v6, 16, v2
	v_mul_f32_e32 v8, 0xbfb8aa3b, v6
	v_exp_f32_e32 v8, v8
	v_and_b32_e32 v2, 0xffff0000, v2
	v_lshlrev_b32_e32 v7, 16, v3
	v_and_b32_e32 v3, 0xffff0000, v3
	v_add_f32_e32 v8, 1.0, v8
	v_rcp_f32_e32 v8, v8
	s_nop 0
	v_mul_f32_e32 v6, v8, v6
	v_mul_f32_e32 v8, v28, v0
	v_mul_f32_e32 v6, v8, v6
	v_mul_f32_e32 v8, 0xbfb8aa3b, v2
	v_exp_f32_e32 v8, v8
	s_nop 0
	v_add_f32_e32 v8, 1.0, v8
	v_rcp_f32_e32 v8, v8
	s_nop 0
	v_mul_f32_e32 v2, v8, v2
	v_mul_f32_e32 v8, v29, v0
	v_mul_f32_e32 v2, v8, v2
	v_mul_f32_e32 v8, 0xbfb8aa3b, v7
	v_exp_f32_e32 v8, v8
	v_mul_f32_e32 v2, 0x41800000, v2
	v_med3_f32 v2, v2, s93, v223
	v_add_f32_e32 v8, 1.0, v8
	v_rcp_f32_e32 v8, v8
	s_nop 0
	v_mul_f32_e32 v7, v8, v7
	v_mul_f32_e32 v8, v30, v0
	v_mul_f32_e32 v7, v8, v7
	v_mul_f32_e32 v8, 0xbfb8aa3b, v3
	v_exp_f32_e32 v8, v8
	v_mul_f32_e32 v0, v31, v0
	v_add_f32_e32 v8, 1.0, v8
	v_rcp_f32_e32 v8, v8
	s_nop 0
	v_mul_f32_e32 v3, v8, v3
	v_mul_f32_e32 v0, v0, v3
	v_mul_f32_e32 v3, 0x41800000, v6
	v_mul_f32_e32 v6, 0x41800000, v7
	v_med3_f32 v3, v3, s93, v223
	v_mov_b32_e32 v215, v1
	v_cvt_pk_fp8_f32 v215, v3, v2
	v_mul_f32_e32 v0, 0x41800000, v0
	v_med3_f32 v2, v6, s93, v223
	v_med3_f32 v0, v0, s93, v223
	v_cvt_pk_fp8_f32 v215, v2, v0 op_sel:[0,0,1]
	s_nop 1
	v_permlane32_swap_b32_e32 v212, v213
	v_permlane32_swap_b32_e32 v214, v215
	global_store_dwordx4 v[216:217], v[212:215], off offset:96

; template <int DQK, int W1, int DV, int VW, int MODE> ...
;     ...
;         f32x16 e0 = s[0], e1 = s[1];
;         if (MODE != 0) { const float nm = -m; e0 = e0 + nm; e1 = e1 + nm; }
; #pragma unroll
;         for (int i = 0; i < 16; ++i) { e0[i] = __builtin_amdgcn_exp2f(e0[i]); e1[i] = __builtin_amdgcn_exp2f(e1[i]); }
;         s[0] = e0; s[1] = e1;
;         const f32x16 sm = e0 + e1;
;         typedef __attribute__((ext_vector_type(8))) float f32x8;
;         const f32x8 h8 = sm.lo + sm.hi;
;         const f32x4 h4 = h8.lo + h8.hi;
;         const f32x2 h2 = h4.lo + h4.hi;
;         l += h2[0] + h2[1];
;       }
;       bf16x8 pb[2][2];
; #pragma unroll
;       for (int n = 0; n < 2; ++n)
; #pragma unroll
;         for (int s2 = 0; s2 < 2; ++s2) {
;           u32x4 pw = {pk2(s[n][8 * s2 + 0], s[n][8 * s2 + 1]), pk2(s[n][8 * s2 + 2], s[n][8 * s2 + 3]),
;                       pk2(s[n][8 * s2 + 4], s[n][8 * s2 + 5]), pk2(s[n][8 * s2 + 6], s[n][8 * s2 + 7])};
;           pb[n][s2] = __builtin_bit_cast(bf16x8, pw);
;         }
;       pv_block<0>(o[0], bufa + vlane, pb);
;       if constexpr (NCB > 1) pv_block<1>(o[1], bufa + vlane, pb);
;       if constexpr (NCB > 2) pv_block<2>(o[2], bufa + vlane, pb);
;       if constexpr (NCB > 3) pv_block<3>(o[3], bufa + vlane, pb);
;     }
;     asm volatile("s_waitcnt vmcnt(0)" ::: "memory");
;     __syncthreads();
.LBB0_1291:
	v_pk_add_f32 v[96:97], v[108:109], v[94:95] op_sel_hi:[1,0]
	v_pk_add_f32 v[98:99], v[106:107], v[94:95] op_sel_hi:[1,0]
	v_pk_add_f32 v[100:101], v[104:105], v[94:95] op_sel_hi:[1,0]
	v_pk_add_f32 v[102:103], v[102:103], v[94:95] op_sel_hi:[1,0]
	v_pk_add_f32 v[72:73], v[72:73], v[94:95] op_sel_hi:[1,0]
	v_pk_add_f32 v[70:71], v[70:71], v[94:95] op_sel_hi:[1,0]
	v_pk_add_f32 v[68:69], v[68:69], v[94:95] op_sel_hi:[1,0]
	v_mov_b32_e32 v95, v94
	v_mov_b64_e32 v[74:75], s[82:83]
	v_pk_add_f32 v[66:67], v[66:67], v[94:95]
	v_pk_add_f32 v[92:93], v[92:93], v[94:95] op_sel_hi:[1,0]
	v_pk_add_f32 v[90:91], v[90:91], v[94:95] op_sel_hi:[1,0]
	v_pk_add_f32 v[86:87], v[86:87], v[94:95] op_sel_hi:[1,0]
	v_pk_add_f32 v[84:85], v[84:85], v[94:95] op_sel_hi:[1,0]
	v_pk_add_f32 v[82:83], v[82:83], v[94:95] op_sel_hi:[1,0]
	v_pk_add_f32 v[80:81], v[80:81], v[94:95] op_sel_hi:[1,0]
	v_pk_add_f32 v[78:79], v[78:79], v[94:95] op_sel_hi:[1,0]
	v_pk_add_f32 v[76:77], v[76:77], v[94:95]
	v_mad_u64_u32 v[74:75], s[0:1], v166, s34, v[74:75]
	v_exp_f32_e32 v66, v66
	v_exp_f32_e32 v76, v76
	v_exp_f32_e32 v67, v67
	v_exp_f32_e32 v77, v77
	v_exp_f32_e32 v68, v68
	v_exp_f32_e32 v78, v78
	v_exp_f32_e32 v69, v69
	v_exp_f32_e32 v79, v79
	v_exp_f32_e32 v70, v70
	v_exp_f32_e32 v80, v80
	v_exp_f32_e32 v71, v71
	v_exp_f32_e32 v81, v81
	v_exp_f32_e32 v72, v72
	v_exp_f32_e32 v82, v82
	v_exp_f32_e32 v73, v73
	v_exp_f32_e32 v83, v83
	v_exp_f32_e32 v94, v102
	v_exp_f32_e32 v84, v84
	v_exp_f32_e32 v95, v103
	v_exp_f32_e32 v85, v85
	v_exp_f32_e32 v100, v100
	v_exp_f32_e32 v86, v86
	v_exp_f32_e32 v101, v101
	v_exp_f32_e32 v87, v87
	v_exp_f32_e32 v98, v98
	v_exp_f32_e32 v90, v90
	v_exp_f32_e32 v99, v99
	v_exp_f32_e32 v91, v91
	v_exp_f32_e32 v96, v96
	v_exp_f32_e32 v92, v92
	v_exp_f32_e32 v97, v97
	v_exp_f32_e32 v93, v93
	v_mad_u32_u24 v75, v167, s34, v75
	v_readlane_b32 s0, v254, 7
	v_lshl_add_u64 v[74:75], v[74:75], 0, s[54:55]
	v_readlane_b32 s1, v254, 8
	s_mov_b32 s69, s55
	s_lshl_b32 s54, s54, 1
	v_lshl_add_u64 v[88:89], v[74:75], 0, s[0:1]
	v_lshl_add_u64 v[74:75], v[164:165], 0, s[68:69]
	v_lshl_add_u64 v[74:75], v[74:75], 0, s[54:55]
	s_lshl_b32 s54, s0, 1
	v_pk_add_f32 v[102:103], v[100:101], v[86:87]
	v_pk_add_f32 v[104:105], v[68:69], v[78:79]
	v_pk_add_f32 v[106:107], v[96:97], v[92:93]
	v_pk_add_f32 v[108:109], v[72:73], v[82:83]
	v_pk_add_f32 v[110:111], v[94:95], v[84:85]
	v_pk_add_f32 v[112:113], v[66:67], v[76:77]
	v_pk_add_f32 v[114:115], v[98:99], v[90:91]
	v_pk_add_f32 v[116:117], v[70:71], v[80:81]
	v_pk_add_f32 v[110:111], v[112:113], v[110:111]
	v_pk_add_f32 v[114:115], v[116:117], v[114:115]
	v_pk_add_f32 v[106:107], v[108:109], v[106:107]
	v_pk_add_f32 v[102:103], v[104:105], v[102:103]
	s_cmp_lg_u32 0, -1
	v_pk_add_f32 v[102:103], v[102:103], v[106:107]
	v_pk_add_f32 v[104:105], v[110:111], v[114:115]
	s_cselect_b32 s0, 0, 0
	v_pk_add_f32 v[102:103], v[104:105], v[102:103]
	v_cvt_pk_bf16_f32 v66, v66, v67
	v_cvt_pk_bf16_f32 v67, v68, v69
	v_cvt_pk_bf16_f32 v68, v70, v71
	v_cvt_pk_bf16_f32 v69, v72, v73
	s_add_i32 s0, s0, 0x10400
	v_add_f32_e32 v0, v102, v103
	v_cvt_pk_bf16_f32 v70, v94, v95
	v_cvt_pk_bf16_f32 v71, v100, v101
	v_cvt_pk_bf16_f32 v72, v98, v99
	v_cvt_pk_bf16_f32 v73, v96, v97
	v_cvt_pk_bf16_f32 v76, v76, v77
	v_cvt_pk_bf16_f32 v77, v78, v79
	v_cvt_pk_bf16_f32 v78, v80, v81
	v_cvt_pk_bf16_f32 v79, v82, v83
	v_cvt_pk_bf16_f32 v80, v84, v85
	v_cvt_pk_bf16_f32 v81, v86, v87
	v_cvt_pk_bf16_f32 v82, v90, v91
	v_cvt_pk_bf16_f32 v83, v92, v93
	v_add_u32_e32 v102, s0, v163
	ds_read_b64_tr_b16 v[98:99], v102 offset:0
	ds_read_b64_tr_b16 v[100:101], v102 offset:0x200
	ds_read_b64_tr_b16 v[94:95], v102 offset:0x400
	ds_read_b64_tr_b16 v[96:97], v102 offset:0x600
	ds_read_b64_tr_b16 v[90:91], v102 offset:0x800
	ds_read_b64_tr_b16 v[92:93], v102 offset:0xa00
	ds_read_b64_tr_b16 v[84:85], v102 offset:0xc00
	ds_read_b64_tr_b16 v[86:87], v102 offset:0xe00
	s_waitcnt lgkmcnt(0)
	v_add_f32_e32 v0, v193, v0
	v_mfma_f32_32x32x16_bf16 v[50:65], v[98:101], v[66:69], v[50:65]
	v_lshl_add_u64 v[74:75], v[74:75], 0, s[54:55]
	s_mov_b64 s[0:1], 0x1000
	v_readlane_b32 s28, v254, 27
	s_movk_i32 s20, 0x600
	v_readlane_b32 s3, v254, 29
	v_readlane_b32 s29, v254, 28
	v_mov_b32_e32 v163, v1
	v_mfma_f32_32x32x16_bf16 v[50:65], v[94:97], v[70:73], v[50:65]
	v_mfma_f32_32x32x16_bf16 v[50:65], v[90:93], v[76:79], v[50:65]
	v_mfma_f32_32x32x16_bf16 v[50:65], v[84:87], v[80:83], v[50:65]
	ds_read_b64_tr_b16 v[98:99], v102 offset:0x1000
	ds_read_b64_tr_b16 v[100:101], v102 offset:0x1200
	ds_read_b64_tr_b16 v[94:95], v102 offset:0x1400
	ds_read_b64_tr_b16 v[96:97], v102 offset:0x1600
	ds_read_b64_tr_b16 v[90:91], v102 offset:0x1800
	ds_read_b64_tr_b16 v[92:93], v102 offset:0x1a00
	ds_read_b64_tr_b16 v[84:85], v102 offset:0x1c00
	ds_read_b64_tr_b16 v[86:87], v102 offset:0x1e00
	s_waitcnt lgkmcnt(0)
	s_nop 0
	v_mfma_f32_32x32x16_bf16 v[34:49], v[98:101], v[66:69], v[34:49]
	v_mfma_f32_32x32x16_bf16 v[34:49], v[94:97], v[70:73], v[34:49]
	v_mfma_f32_32x32x16_bf16 v[34:49], v[90:93], v[76:79], v[34:49]
	v_mfma_f32_32x32x16_bf16 v[34:49], v[84:87], v[80:83], v[34:49]
	ds_read_b64_tr_b16 v[98:99], v102 offset:0x2000
	ds_read_b64_tr_b16 v[100:101], v102 offset:0x2200
	ds_read_b64_tr_b16 v[94:95], v102 offset:0x2400
	ds_read_b64_tr_b16 v[96:97], v102 offset:0x2600
	ds_read_b64_tr_b16 v[90:91], v102 offset:0x2800
	ds_read_b64_tr_b16 v[92:93], v102 offset:0x2a00
	ds_read_b64_tr_b16 v[84:85], v102 offset:0x2c00
	ds_read_b64_tr_b16 v[86:87], v102 offset:0x2e00
	s_waitcnt lgkmcnt(0)
	s_nop 0
	v_mfma_f32_32x32x16_bf16 v[18:33], v[98:101], v[66:69], v[18:33]
	v_mfma_f32_32x32x16_bf16 v[18:33], v[94:97], v[70:73], v[18:33]
	v_mfma_f32_32x32x16_bf16 v[18:33], v[90:93], v[76:79], v[18:33]
	v_mfma_f32_32x32x16_bf16 v[18:33], v[84:87], v[80:83], v[18:33]
	ds_read_b64_tr_b16 v[98:99], v102 offset:0x3000
	ds_read_b64_tr_b16 v[100:101], v102 offset:0x3200
	ds_read_b64_tr_b16 v[94:95], v102 offset:0x3400
	ds_read_b64_tr_b16 v[96:97], v102 offset:0x3600
	ds_read_b64_tr_b16 v[90:91], v102 offset:0x3800
	ds_read_b64_tr_b16 v[92:93], v102 offset:0x3a00
	ds_read_b64_tr_b16 v[84:85], v102 offset:0x3c00
	ds_read_b64_tr_b16 v[86:87], v102 offset:0x3e00
	s_waitcnt lgkmcnt(0)
	s_waitcnt vmcnt(0)
	s_barrier
; DI float bf2f(unsigned b) { return __uint_as_float(b << 16); }
; template <int DQK, int W1, int DV, int VW, int MODE> ...
;     ...
;       pv_block<0>(o[0], bufa + vlane, pb);
;       if constexpr (NCB > 1) pv_block<1>(o[1], bufa + vlane, pb);
;       if constexpr (NCB > 2) pv_block<2>(o[2], bufa + vlane, pb);
;       if constexpr (NCB > 3) pv_block<3>(o[3], bufa + vlane, pb);
;     }
;     asm volatile("s_waitcnt vmcnt(0)" ::: "memory");
;     __syncthreads();
;   }
;   const float inv = __builtin_amdgcn_rcpf(xhalf_sum(l));
;   u32x2 ggv[NCB * 4];
; #pragma unroll
;   for (int cb = 0; cb < NCB; ++cb)
; #pragma unroll
;     for (int g = 0; g < 4; ++g) ggv[cb * 4 + g] = *(const u32x2*)(grow + 32 * cb + 8 * g + 4 * hi);
;   __builtin_amdgcn_sched_barrier(0);
; #pragma unroll
;   for (int cb = 0; cb < NCB; ++cb)
; #pragma unroll
;     for (int g = 0; g < 4; ++g) {
;       const int dv = 32 * cb + 8 * g + 4 * hi;
;       const u32x2 gg = ggv[cb * 4 + g];
;       float gv[4] = {bf2f(gg[0] & 0xffffu), bf2f(gg[0] >> 16), bf2f(gg[1] & 0xffffu), bf2f(gg[1] >> 16)};
;       float ov[4];
; #pragma unroll
;       for (int j = 0; j < 4; ++j) {
;         const float sg = gv[j] * __builtin_amdgcn_rcpf(1.f + __builtin_amdgcn_exp2f(-LOG2E * gv[j]));
;         ov[j] = o[cb][4 * g + j] * inv * sg;
;       }
;       *(unsigned*)((unsigned char*)yrow + dv) = pk4_fp8(ov[0] * Y_SCALE, ov[1] * Y_SCALE, ov[2] * Y_SCALE, ov[3] * Y_SCALE);
;       __builtin_amdgcn_sched_barrier(0);
;     }
	v_mfma_f32_32x32x16_bf16 v[2:17], v[98:101], v[66:69], v[2:17]
	v_mov_b32_e32 v66, v0
	s_nop 1
	v_permlane32_swap_b32_e32 v0, v66
	v_add_f32_e32 v102, v0, v66
	v_lshlrev_b32_e32 v0, 1, v162
	v_lshl_add_u64 v[66:67], v[74:75], 0, v[0:1]
	v_lshl_add_u64 v[98:99], v[66:67], 0, s[0:1]
	v_mfma_f32_32x32x16_bf16 v[2:17], v[94:97], v[70:73], v[2:17]
	s_movk_i32 s0, 0x1000
	v_add_co_u32_e32 v66, vcc, s0, v66
	v_rcp_f32_e32 v0, v102
	s_nop 0
	v_addc_co_u32_e32 v67, vcc, 0, v67, vcc
	v_mfma_f32_32x32x16_bf16 v[2:17], v[90:93], v[76:79], v[2:17]
	v_mfma_f32_32x32x16_bf16 v[2:17], v[84:87], v[80:83], v[2:17]
	v_bfe_i32 v211, v179, 5, 1
	v_mul_i32_i24_e32 v210, 24, v211
	v_lshl_add_u64 v[208:209], v[98:99], 0, v[210:211]
	global_load_dwordx2 v[100:101], v[66:67], off
	global_load_dwordx4 v[94:97], v[208:209], off offset:32
	global_load_dwordx4 v[90:93], v[208:209], off offset:64
	global_load_dwordx4 v[84:87], v[208:209], off offset:96
	global_load_dwordx4 v[80:83], v[208:209], off offset:128
	global_load_dwordx4 v[76:79], v[208:209], off offset:160
	global_load_dwordx4 v[72:75], v[208:209], off offset:192
	global_load_dwordx4 v[68:71], v[208:209], off offset:224
	global_load_dwordx2 v[66:67], v[98:99], off offset:240
	s_waitcnt vmcnt(8)
	v_lshlrev_b32_e32 v98, 16, v100
	v_mul_f32_e32 v102, 0xbfb8aa3b, v98
	v_exp_f32_e32 v102, v102
	v_and_b32_e32 v99, 0xffff0000, v100
	v_mul_f32_e32 v50, v50, v0
	v_lshlrev_b32_e32 v100, 16, v101
	v_add_f32_e32 v102, 1.0, v102
	v_rcp_f32_e32 v102, v102
	v_mul_f32_e32 v51, v51, v0
	v_and_b32_e32 v101, 0xffff0000, v101
	v_mul_f32_e32 v52, v52, v0
	v_mul_f32_e32 v98, v102, v98
	v_mul_f32_e32 v50, v50, v98
	v_mul_f32_e32 v98, 0xbfb8aa3b, v99
	v_exp_f32_e32 v98, v98
	v_mul_f32_e32 v53, v53, v0
	v_mul_f32_e32 v50, 0x41800000, v50
	v_med3_f32 v50, v50, s93, v223
	v_add_f32_e32 v98, 1.0, v98
	v_rcp_f32_e32 v98, v98
	s_nop 0
	v_mul_f32_e32 v98, v98, v99
	v_mul_f32_e32 v51, v51, v98
	v_mul_f32_e32 v98, 0xbfb8aa3b, v100
	v_exp_f32_e32 v98, v98
	v_mul_f32_e32 v51, 0x41800000, v51
	v_med3_f32 v51, v51, s93, v223
	v_add_f32_e32 v98, 1.0, v98
	v_rcp_f32_e32 v98, v98
	s_nop 0
	v_mul_f32_e32 v98, v98, v100
	v_mul_f32_e32 v52, v52, v98
	v_mul_f32_e32 v98, 0xbfb8aa3b, v101
	v_exp_f32_e32 v98, v98
	v_mul_f32_e32 v52, 0x41800000, v52
	v_add_f32_e32 v98, 1.0, v98
	v_rcp_f32_e32 v98, v98
	s_nop 0
	v_mul_f32_e32 v98, v98, v101
	v_mul_f32_e32 v53, v53, v98
	v_mov_b32_e32 v212, v1
	v_cvt_pk_fp8_f32 v212, v50, v51
	v_mul_f32_e32 v53, 0x41800000, v53
	v_med3_f32 v50, v52, s93, v223
	v_med3_f32 v51, v53, s93, v223
	v_cvt_pk_fp8_f32 v212, v50, v51 op_sel:[0,0,1]
	v_lshl_add_u64 v[50:51], v[88:89], 0, v[162:163]
	s_waitcnt vmcnt(7)
	v_permlane32_swap_b32_e32 v94, v96
	v_permlane32_swap_b32_e32 v95, v97
	v_lshlrev_b32_e32 v52, 16, v96
	v_and_b32_e32 v53, 0xffff0000, v96
	v_mul_f32_e32 v96, 0xbfb8aa3b, v52
	v_exp_f32_e32 v96, v96
	v_mul_f32_e32 v54, v54, v0
	v_lshlrev_b32_e32 v88, 16, v97
	v_and_b32_e32 v89, 0xffff0000, v97
	v_add_f32_e32 v96, 1.0, v96
	v_rcp_f32_e32 v96, v96
	s_nop 0
	v_mul_f32_e32 v52, v96, v52
	v_mul_f32_e32 v52, v54, v52
	v_mul_f32_e32 v54, 0xbfb8aa3b, v53
	v_exp_f32_e32 v54, v54
	v_mul_f32_e32 v52, 0x41800000, v52
	v_med3_f32 v52, v52, s93, v223
	v_add_f32_e32 v54, 1.0, v54
	v_rcp_f32_e32 v54, v54
	s_nop 0
	v_mul_f32_e32 v53, v54, v53
	v_mul_f32_e32 v54, v55, v0
	v_mul_f32_e32 v53, v54, v53
	v_mul_f32_e32 v54, 0xbfb8aa3b, v88
	v_exp_f32_e32 v54, v54
	v_mul_f32_e32 v55, v56, v0
	v_mul_f32_e32 v56, v57, v0
	v_mul_f32_e32 v53, 0x41800000, v53
	v_add_f32_e32 v54, 1.0, v54
	v_rcp_f32_e32 v54, v54
	v_med3_f32 v53, v53, s93, v223
	v_mul_f32_e32 v54, v54, v88
	v_mul_f32_e32 v54, v55, v54
	v_mul_f32_e32 v55, 0xbfb8aa3b, v89
	v_exp_f32_e32 v55, v55
	v_mul_f32_e32 v54, 0x41800000, v54
	v_add_f32_e32 v55, 1.0, v55
	v_rcp_f32_e32 v55, v55
	s_nop 0
	v_mul_f32_e32 v55, v55, v89
	v_mul_f32_e32 v55, v56, v55
	v_mov_b32_e32 v214, v1
	v_cvt_pk_fp8_f32 v214, v52, v53
	v_mul_f32_e32 v55, 0x41800000, v55
	v_med3_f32 v52, v54, s93, v223
	v_med3_f32 v53, v55, s93, v223
	v_cvt_pk_fp8_f32 v214, v52, v53 op_sel:[0,0,1]
	s_waitcnt vmcnt(7)
	v_lshlrev_b32_e32 v52, 16, v94
	v_mul_f32_e32 v56, 0xbfb8aa3b, v52
	v_exp_f32_e32 v56, v56
	v_and_b32_e32 v53, 0xffff0000, v94
	v_lshlrev_b32_e32 v54, 16, v95
	v_and_b32_e32 v55, 0xffff0000, v95
	v_add_f32_e32 v56, 1.0, v56
	v_rcp_f32_e32 v56, v56
	s_nop 0
	v_mul_f32_e32 v52, v56, v52
	v_mul_f32_e32 v56, v58, v0
	v_mul_f32_e32 v52, v56, v52
	v_mul_f32_e32 v56, 0xbfb8aa3b, v53
	v_exp_f32_e32 v56, v56
	v_mul_f32_e32 v52, 0x41800000, v52
	v_med3_f32 v52, v52, s93, v223
	v_add_f32_e32 v56, 1.0, v56
	v_rcp_f32_e32 v56, v56
	s_nop 0
	v_mul_f32_e32 v53, v56, v53
	v_mul_f32_e32 v56, v59, v0
	v_mul_f32_e32 v53, v56, v53
	v_mul_f32_e32 v56, 0xbfb8aa3b, v54
	v_exp_f32_e32 v56, v56
	v_mul_f32_e32 v53, 0x41800000, v53
	v_med3_f32 v53, v53, s93, v223
	v_add_f32_e32 v56, 1.0, v56
	v_rcp_f32_e32 v56, v56
	s_nop 0
	v_mul_f32_e32 v54, v56, v54
	v_mul_f32_e32 v56, v60, v0
	v_mul_f32_e32 v54, v56, v54
	v_mul_f32_e32 v56, 0xbfb8aa3b, v55
	v_exp_f32_e32 v56, v56
	v_mul_f32_e32 v54, 0x41800000, v54
	v_add_f32_e32 v56, 1.0, v56
	v_rcp_f32_e32 v56, v56
	s_nop 0
	v_mul_f32_e32 v55, v56, v55
	v_mul_f32_e32 v56, v61, v0
	v_mul_f32_e32 v55, v56, v55
	v_mov_b32_e32 v213, v1
	v_cvt_pk_fp8_f32 v213, v52, v53
	v_mul_f32_e32 v55, 0x41800000, v55
	v_med3_f32 v52, v54, s93, v223
	v_med3_f32 v53, v55, s93, v223
	v_cvt_pk_fp8_f32 v213, v52, v53 op_sel:[0,0,1]
	s_waitcnt vmcnt(6)
; DI float bf2f(unsigned b) { return __uint_as_float(b << 16); }
; template <int DQK, int W1, int DV, int VW, int MODE> ...
;     ...
; #pragma unroll
;   for (int cb = 0; cb < NCB; ++cb)
; #pragma unroll
;     for (int g = 0; g < 4; ++g) {
;       const int dv = 32 * cb + 8 * g + 4 * hi;
;       const u32x2 gg = ggv[cb * 4 + g];
;       float gv[4] = {bf2f(gg[0] & 0xffffu), bf2f(gg[0] >> 16), bf2f(gg[1] & 0xffffu), bf2f(gg[1] >> 16)};
;       float ov[4];
; #pragma unroll
;       for (int j = 0; j < 4; ++j) {
;         const float sg = gv[j] * __builtin_amdgcn_rcpf(1.f + __builtin_amdgcn_exp2f(-LOG2E * gv[j]));
;         ov[j] = o[cb][4 * g + j] * inv * sg;
;       }
;       *(unsigned*)((unsigned char*)yrow + dv) = pk4_fp8(ov[0] * Y_SCALE, ov[1] * Y_SCALE, ov[2] * Y_SCALE, ov[3] * Y_SCALE);
;       __builtin_amdgcn_sched_barrier(0);
;     }
	v_permlane32_swap_b32_e32 v90, v92
	v_permlane32_swap_b32_e32 v91, v93
	v_lshlrev_b32_e32 v52, 16, v92
	v_mul_f32_e32 v56, 0xbfb8aa3b, v52
	v_exp_f32_e32 v56, v56
	v_and_b32_e32 v53, 0xffff0000, v92
	v_lshlrev_b32_e32 v54, 16, v93
	v_and_b32_e32 v55, 0xffff0000, v93
	v_add_f32_e32 v56, 1.0, v56
	v_rcp_f32_e32 v56, v56
	s_nop 0
	v_mul_f32_e32 v52, v56, v52
	v_mul_f32_e32 v56, v62, v0
	v_mul_f32_e32 v52, v56, v52
	v_mul_f32_e32 v56, 0xbfb8aa3b, v53
	v_exp_f32_e32 v56, v56
	v_mul_f32_e32 v52, 0x41800000, v52
	v_med3_f32 v52, v52, s93, v223
	v_add_f32_e32 v56, 1.0, v56
	v_rcp_f32_e32 v56, v56
	s_nop 0
	v_mul_f32_e32 v53, v56, v53
	v_mul_f32_e32 v56, v63, v0
	v_mul_f32_e32 v53, v56, v53
	v_mul_f32_e32 v56, 0xbfb8aa3b, v54
	v_exp_f32_e32 v56, v56
	v_mul_f32_e32 v53, 0x41800000, v53
	v_med3_f32 v53, v53, s93, v223
	v_add_f32_e32 v56, 1.0, v56
	v_rcp_f32_e32 v56, v56
	s_nop 0
	v_mul_f32_e32 v54, v56, v54
	v_mul_f32_e32 v56, v64, v0
	v_mul_f32_e32 v54, v56, v54
	v_mul_f32_e32 v56, 0xbfb8aa3b, v55
	v_exp_f32_e32 v56, v56
	v_mul_f32_e32 v54, 0x41800000, v54
	v_add_f32_e32 v56, 1.0, v56
	v_rcp_f32_e32 v56, v56
	s_nop 0
	v_mul_f32_e32 v55, v56, v55
	v_mul_f32_e32 v56, v65, v0
	v_mul_f32_e32 v55, v56, v55
	v_mov_b32_e32 v215, v1
	v_cvt_pk_fp8_f32 v215, v52, v53
	v_mul_f32_e32 v55, 0x41800000, v55
	v_med3_f32 v52, v54, s93, v223
	v_med3_f32 v53, v55, s93, v223
	v_cvt_pk_fp8_f32 v215, v52, v53 op_sel:[0,0,1]
	v_and_b32_e32 v242, 32, v179
	v_lshrrev_b32_e32 v242, 3, v242
	v_lshl_add_u32 v242, v242, 1, v242
	v_mov_b32_e32 v243, 0
	v_lshl_add_u64 v[216:217], v[50:51], 0, v[242:243]
	s_nop 1
	v_permlane32_swap_b32_e32 v212, v213
	v_permlane32_swap_b32_e32 v214, v215
	global_store_dwordx4 v[216:217], v[212:215], off offset:2048
	s_waitcnt vmcnt(7)
	v_lshlrev_b32_e32 v52, 16, v90
	v_mul_f32_e32 v56, 0xbfb8aa3b, v52
	v_exp_f32_e32 v56, v56
	v_and_b32_e32 v53, 0xffff0000, v90
	v_mul_f32_e32 v34, v34, v0
	v_lshlrev_b32_e32 v54, 16, v91
	v_add_f32_e32 v56, 1.0, v56
	v_rcp_f32_e32 v56, v56
	v_mul_f32_e32 v35, v35, v0
	v_and_b32_e32 v55, 0xffff0000, v91
	v_mul_f32_e32 v36, v36, v0
	v_mul_f32_e32 v52, v56, v52
	v_mul_f32_e32 v34, v34, v52
	v_mul_f32_e32 v52, 0xbfb8aa3b, v53
	v_exp_f32_e32 v52, v52
	v_mul_f32_e32 v37, v37, v0
	v_mul_f32_e32 v34, 0x41800000, v34
	v_med3_f32 v34, v34, s93, v223
	v_add_f32_e32 v52, 1.0, v52
	v_rcp_f32_e32 v52, v52
	s_nop 0
	v_mul_f32_e32 v52, v52, v53
	v_mul_f32_e32 v35, v35, v52
	v_mul_f32_e32 v52, 0xbfb8aa3b, v54
	v_exp_f32_e32 v52, v52
	v_mul_f32_e32 v35, 0x41800000, v35
	v_med3_f32 v35, v35, s93, v223
	v_add_f32_e32 v52, 1.0, v52
	v_rcp_f32_e32 v52, v52
	s_nop 0
	v_mul_f32_e32 v52, v52, v54
	v_mul_f32_e32 v36, v36, v52
	v_mul_f32_e32 v52, 0xbfb8aa3b, v55
	v_exp_f32_e32 v52, v52
	v_mul_f32_e32 v36, 0x41800000, v36
	v_add_f32_e32 v52, 1.0, v52
	v_rcp_f32_e32 v52, v52
	s_nop 0
	v_mul_f32_e32 v52, v52, v55
	v_mul_f32_e32 v37, v37, v52
	v_mov_b32_e32 v212, v1
	v_cvt_pk_fp8_f32 v212, v34, v35
	v_mul_f32_e32 v37, 0x41800000, v37
	v_med3_f32 v34, v36, s93, v223
	v_med3_f32 v35, v37, s93, v223
	v_cvt_pk_fp8_f32 v212, v34, v35 op_sel:[0,0,1]
	s_waitcnt vmcnt(6)
	v_permlane32_swap_b32_e32 v84, v86
	v_permlane32_swap_b32_e32 v85, v87
	v_lshlrev_b32_e32 v34, 16, v86
	v_mul_f32_e32 v52, 0xbfb8aa3b, v34
	v_exp_f32_e32 v52, v52
	v_and_b32_e32 v35, 0xffff0000, v86
	v_mul_f32_e32 v38, v38, v0
	v_lshlrev_b32_e32 v36, 16, v87
	v_add_f32_e32 v52, 1.0, v52
	v_rcp_f32_e32 v52, v52
	v_and_b32_e32 v37, 0xffff0000, v87
	v_mul_f32_e32 v34, v52, v34
	v_mul_f32_e32 v34, v38, v34
	v_mul_f32_e32 v38, 0xbfb8aa3b, v35
	v_exp_f32_e32 v38, v38
	v_mul_f32_e32 v34, 0x41800000, v34
	v_med3_f32 v34, v34, s93, v223
	v_add_f32_e32 v38, 1.0, v38
	v_rcp_f32_e32 v38, v38
	s_nop 0
	v_mul_f32_e32 v35, v38, v35
	v_mul_f32_e32 v38, v39, v0
	v_mul_f32_e32 v35, v38, v35
	v_mul_f32_e32 v38, 0xbfb8aa3b, v36
	v_exp_f32_e32 v38, v38
	v_mul_f32_e32 v35, 0x41800000, v35
	v_med3_f32 v35, v35, s93, v223
	v_add_f32_e32 v38, 1.0, v38
	v_rcp_f32_e32 v38, v38
	s_nop 0
	v_mul_f32_e32 v36, v38, v36
	v_mul_f32_e32 v38, v40, v0
	v_mul_f32_e32 v36, v38, v36
	v_mul_f32_e32 v38, 0xbfb8aa3b, v37
	v_exp_f32_e32 v38, v38
	v_mul_f32_e32 v36, 0x41800000, v36
	v_add_f32_e32 v38, 1.0, v38
	v_rcp_f32_e32 v38, v38
	s_nop 0
	v_mul_f32_e32 v37, v38, v37
	v_mul_f32_e32 v38, v41, v0
	v_mul_f32_e32 v37, v38, v37
	v_mov_b32_e32 v214, v1
	v_cvt_pk_fp8_f32 v214, v34, v35
	v_mul_f32_e32 v37, 0x41800000, v37
	v_med3_f32 v34, v36, s93, v223
	v_med3_f32 v35, v37, s93, v223
	v_cvt_pk_fp8_f32 v214, v34, v35 op_sel:[0,0,1]
	s_waitcnt vmcnt(6)
	v_lshlrev_b32_e32 v34, 16, v84
	v_mul_f32_e32 v38, 0xbfb8aa3b, v34
	v_exp_f32_e32 v38, v38
	v_and_b32_e32 v35, 0xffff0000, v84
	v_lshlrev_b32_e32 v36, 16, v85
	v_and_b32_e32 v37, 0xffff0000, v85
	v_add_f32_e32 v38, 1.0, v38
	v_rcp_f32_e32 v38, v38
	s_nop 0
	v_mul_f32_e32 v34, v38, v34
	v_mul_f32_e32 v38, v42, v0
	v_mul_f32_e32 v34, v38, v34
	v_mul_f32_e32 v38, 0xbfb8aa3b, v35
	v_exp_f32_e32 v38, v38
	v_mul_f32_e32 v34, 0x41800000, v34
	v_med3_f32 v34, v34, s93, v223
	v_add_f32_e32 v38, 1.0, v38
	v_rcp_f32_e32 v38, v38
	s_nop 0
	v_mul_f32_e32 v35, v38, v35
	v_mul_f32_e32 v38, v43, v0
	v_mul_f32_e32 v35, v38, v35
	v_mul_f32_e32 v38, 0xbfb8aa3b, v36
	v_exp_f32_e32 v38, v38
	v_mul_f32_e32 v35, 0x41800000, v35
	v_med3_f32 v35, v35, s93, v223
	v_add_f32_e32 v38, 1.0, v38
	v_rcp_f32_e32 v38, v38
	s_nop 0
	v_mul_f32_e32 v36, v38, v36
	v_mul_f32_e32 v38, v44, v0
	v_mul_f32_e32 v36, v38, v36
	v_mul_f32_e32 v38, 0xbfb8aa3b, v37
	v_exp_f32_e32 v38, v38
	v_mul_f32_e32 v36, 0x41800000, v36
	v_add_f32_e32 v38, 1.0, v38
	v_rcp_f32_e32 v38, v38
	s_nop 0
	v_mul_f32_e32 v37, v38, v37
	v_mul_f32_e32 v38, v45, v0
	v_mul_f32_e32 v37, v38, v37
	v_mov_b32_e32 v213, v1
	v_cvt_pk_fp8_f32 v213, v34, v35
	v_mul_f32_e32 v37, 0x41800000, v37
	v_med3_f32 v34, v36, s93, v223
	v_med3_f32 v35, v37, s93, v223
	v_cvt_pk_fp8_f32 v213, v34, v35 op_sel:[0,0,1]
	s_waitcnt vmcnt(5)
; DI float bf2f(unsigned b) { return __uint_as_float(b << 16); }
; template <int DQK, int W1, int DV, int VW, int MODE> ...
;     ...
; #pragma unroll
;   for (int cb = 0; cb < NCB; ++cb)
; #pragma unroll
;     for (int g = 0; g < 4; ++g) {
;       const int dv = 32 * cb + 8 * g + 4 * hi;
;       const u32x2 gg = ggv[cb * 4 + g];
;       float gv[4] = {bf2f(gg[0] & 0xffffu), bf2f(gg[0] >> 16), bf2f(gg[1] & 0xffffu), bf2f(gg[1] >> 16)};
;       float ov[4];
; #pragma unroll
;       for (int j = 0; j < 4; ++j) {
;         const float sg = gv[j] * __builtin_amdgcn_rcpf(1.f + __builtin_amdgcn_exp2f(-LOG2E * gv[j]));
;         ov[j] = o[cb][4 * g + j] * inv * sg;
;       }
;       *(unsigned*)((unsigned char*)yrow + dv) = pk4_fp8(ov[0] * Y_SCALE, ov[1] * Y_SCALE, ov[2] * Y_SCALE, ov[3] * Y_SCALE);
;       __builtin_amdgcn_sched_barrier(0);
;     }
	v_permlane32_swap_b32_e32 v80, v82
	v_permlane32_swap_b32_e32 v81, v83
	v_lshlrev_b32_e32 v34, 16, v82
	v_mul_f32_e32 v38, 0xbfb8aa3b, v34
	v_exp_f32_e32 v38, v38
	v_and_b32_e32 v35, 0xffff0000, v82
	v_lshlrev_b32_e32 v36, 16, v83
	v_and_b32_e32 v37, 0xffff0000, v83
	v_add_f32_e32 v38, 1.0, v38
	v_rcp_f32_e32 v38, v38
	s_nop 0
	v_mul_f32_e32 v34, v38, v34
	v_mul_f32_e32 v38, v46, v0
	v_mul_f32_e32 v34, v38, v34
	v_mul_f32_e32 v38, 0xbfb8aa3b, v35
	v_exp_f32_e32 v38, v38
	v_mul_f32_e32 v34, 0x41800000, v34
	v_med3_f32 v34, v34, s93, v223
	v_add_f32_e32 v38, 1.0, v38
	v_rcp_f32_e32 v38, v38
	s_nop 0
	v_mul_f32_e32 v35, v38, v35
	v_mul_f32_e32 v38, v47, v0
	v_mul_f32_e32 v35, v38, v35
	v_mul_f32_e32 v38, 0xbfb8aa3b, v36
	v_exp_f32_e32 v38, v38
	v_mul_f32_e32 v35, 0x41800000, v35
	v_med3_f32 v35, v35, s93, v223
	v_add_f32_e32 v38, 1.0, v38
	v_rcp_f32_e32 v38, v38
	s_nop 0
	v_mul_f32_e32 v36, v38, v36
	v_mul_f32_e32 v38, v48, v0
	v_mul_f32_e32 v36, v38, v36
	v_mul_f32_e32 v38, 0xbfb8aa3b, v37
	v_exp_f32_e32 v38, v38
	v_mul_f32_e32 v36, 0x41800000, v36
	v_add_f32_e32 v38, 1.0, v38
	v_rcp_f32_e32 v38, v38
	s_nop 0
	v_mul_f32_e32 v37, v38, v37
	v_mul_f32_e32 v38, v49, v0
	v_mul_f32_e32 v37, v38, v37
	v_mov_b32_e32 v215, v1
	v_cvt_pk_fp8_f32 v215, v34, v35
	v_mul_f32_e32 v37, 0x41800000, v37
	v_med3_f32 v34, v36, s93, v223
	v_med3_f32 v35, v37, s93, v223
	v_cvt_pk_fp8_f32 v215, v34, v35 op_sel:[0,0,1]
	s_nop 1
	v_permlane32_swap_b32_e32 v212, v213
	v_permlane32_swap_b32_e32 v214, v215
	global_store_dwordx4 v[216:217], v[212:215], off offset:2080
	s_waitcnt vmcnt(6)
	v_lshlrev_b32_e32 v34, 16, v80
	v_mul_f32_e32 v38, 0xbfb8aa3b, v34
	v_exp_f32_e32 v38, v38
	v_and_b32_e32 v35, 0xffff0000, v80
	v_mul_f32_e32 v18, v18, v0
	v_lshlrev_b32_e32 v36, 16, v81
	v_add_f32_e32 v38, 1.0, v38
	v_rcp_f32_e32 v38, v38
	v_mul_f32_e32 v19, v19, v0
	v_and_b32_e32 v37, 0xffff0000, v81
	v_mul_f32_e32 v20, v20, v0
	v_mul_f32_e32 v34, v38, v34
	v_mul_f32_e32 v18, v18, v34
	v_mul_f32_e32 v34, 0xbfb8aa3b, v35
	v_exp_f32_e32 v34, v34
	v_mul_f32_e32 v21, v21, v0
	v_mul_f32_e32 v18, 0x41800000, v18
	v_med3_f32 v18, v18, s93, v223
	v_add_f32_e32 v34, 1.0, v34
	v_rcp_f32_e32 v34, v34
	s_nop 0
	v_mul_f32_e32 v34, v34, v35
	v_mul_f32_e32 v19, v19, v34
	v_mul_f32_e32 v34, 0xbfb8aa3b, v36
	v_exp_f32_e32 v34, v34
	v_mul_f32_e32 v19, 0x41800000, v19
	v_med3_f32 v19, v19, s93, v223
	v_add_f32_e32 v34, 1.0, v34
	v_rcp_f32_e32 v34, v34
	s_nop 0
	v_mul_f32_e32 v34, v34, v36
	v_mul_f32_e32 v20, v20, v34
	v_mul_f32_e32 v34, 0xbfb8aa3b, v37
	v_exp_f32_e32 v34, v34
	v_mul_f32_e32 v20, 0x41800000, v20
	v_add_f32_e32 v34, 1.0, v34
	v_rcp_f32_e32 v34, v34
	s_nop 0
	v_mul_f32_e32 v34, v34, v37
	v_mul_f32_e32 v21, v21, v34
	v_mov_b32_e32 v212, v1
	v_cvt_pk_fp8_f32 v212, v18, v19
	v_mul_f32_e32 v21, 0x41800000, v21
	v_med3_f32 v18, v20, s93, v223
	v_med3_f32 v19, v21, s93, v223
	v_cvt_pk_fp8_f32 v212, v18, v19 op_sel:[0,0,1]
	s_waitcnt vmcnt(5)
	v_permlane32_swap_b32_e32 v76, v78
	v_permlane32_swap_b32_e32 v77, v79
	v_lshlrev_b32_e32 v18, 16, v78
	v_mul_f32_e32 v34, 0xbfb8aa3b, v18
	v_exp_f32_e32 v34, v34
	v_and_b32_e32 v19, 0xffff0000, v78
	v_mul_f32_e32 v22, v22, v0
	v_lshlrev_b32_e32 v20, 16, v79
	v_add_f32_e32 v34, 1.0, v34
	v_rcp_f32_e32 v34, v34
	v_and_b32_e32 v21, 0xffff0000, v79
	v_mul_f32_e32 v18, v34, v18
	v_mul_f32_e32 v18, v22, v18
	v_mul_f32_e32 v22, 0xbfb8aa3b, v19
	v_exp_f32_e32 v22, v22
	v_mul_f32_e32 v18, 0x41800000, v18
	v_med3_f32 v18, v18, s93, v223
	v_add_f32_e32 v22, 1.0, v22
	v_rcp_f32_e32 v22, v22
	s_nop 0
	v_mul_f32_e32 v19, v22, v19
	v_mul_f32_e32 v22, v23, v0
	v_mul_f32_e32 v19, v22, v19
	v_mul_f32_e32 v22, 0xbfb8aa3b, v20
	v_exp_f32_e32 v22, v22
	v_mul_f32_e32 v19, 0x41800000, v19
	v_med3_f32 v19, v19, s93, v223
	v_add_f32_e32 v22, 1.0, v22
	v_rcp_f32_e32 v22, v22
	s_nop 0
	v_mul_f32_e32 v20, v22, v20
	v_mul_f32_e32 v22, v24, v0
	v_mul_f32_e32 v20, v22, v20
	v_mul_f32_e32 v22, 0xbfb8aa3b, v21
	v_exp_f32_e32 v22, v22
	v_mul_f32_e32 v20, 0x41800000, v20
	v_add_f32_e32 v22, 1.0, v22
	v_rcp_f32_e32 v22, v22
	s_nop 0
	v_mul_f32_e32 v21, v22, v21
	v_mul_f32_e32 v22, v25, v0
	v_mul_f32_e32 v21, v22, v21
	v_mov_b32_e32 v214, v1
	v_cvt_pk_fp8_f32 v214, v18, v19
	v_mul_f32_e32 v21, 0x41800000, v21
	v_med3_f32 v18, v20, s93, v223
	v_med3_f32 v19, v21, s93, v223
	v_cvt_pk_fp8_f32 v214, v18, v19 op_sel:[0,0,1]
	s_waitcnt vmcnt(5)
	v_lshlrev_b32_e32 v18, 16, v76
	v_mul_f32_e32 v22, 0xbfb8aa3b, v18
	v_exp_f32_e32 v22, v22
	v_and_b32_e32 v19, 0xffff0000, v76
	v_lshlrev_b32_e32 v20, 16, v77
	v_and_b32_e32 v21, 0xffff0000, v77
	v_add_f32_e32 v22, 1.0, v22
	v_rcp_f32_e32 v22, v22
	s_nop 0
	v_mul_f32_e32 v18, v22, v18
	v_mul_f32_e32 v22, v26, v0
	v_mul_f32_e32 v18, v22, v18
	v_mul_f32_e32 v22, 0xbfb8aa3b, v19
	v_exp_f32_e32 v22, v22
	v_mul_f32_e32 v18, 0x41800000, v18
	v_med3_f32 v18, v18, s93, v223
	v_add_f32_e32 v22, 1.0, v22
	v_rcp_f32_e32 v22, v22
	s_nop 0
	v_mul_f32_e32 v19, v22, v19
	v_mul_f32_e32 v22, v27, v0
	v_mul_f32_e32 v19, v22, v19
	v_mul_f32_e32 v22, 0xbfb8aa3b, v20
	v_exp_f32_e32 v22, v22
	v_mul_f32_e32 v19, 0x41800000, v19
	v_med3_f32 v19, v19, s93, v223
	v_add_f32_e32 v22, 1.0, v22
	v_rcp_f32_e32 v22, v22
	s_nop 0
	v_mul_f32_e32 v20, v22, v20
	v_mul_f32_e32 v22, v28, v0
	v_mul_f32_e32 v20, v22, v20
	v_mul_f32_e32 v22, 0xbfb8aa3b, v21
	v_exp_f32_e32 v22, v22
	v_mul_f32_e32 v20, 0x41800000, v20
	v_add_f32_e32 v22, 1.0, v22
	v_rcp_f32_e32 v22, v22
	s_nop 0
	v_mul_f32_e32 v21, v22, v21
	v_mul_f32_e32 v22, v29, v0
	v_mul_f32_e32 v21, v22, v21
	v_mov_b32_e32 v213, v1
	v_cvt_pk_fp8_f32 v213, v18, v19
	v_mul_f32_e32 v21, 0x41800000, v21
	v_med3_f32 v18, v20, s93, v223
	v_med3_f32 v19, v21, s93, v223
	v_cvt_pk_fp8_f32 v213, v18, v19 op_sel:[0,0,1]
	s_waitcnt vmcnt(4)
; DI float bf2f(unsigned b) { return __uint_as_float(b << 16); }
; template <int DQK, int W1, int DV, int VW, int MODE> ...
;     ...
; #pragma unroll
;   for (int cb = 0; cb < NCB; ++cb)
; #pragma unroll
;     for (int g = 0; g < 4; ++g) {
;       const int dv = 32 * cb + 8 * g + 4 * hi;
;       const u32x2 gg = ggv[cb * 4 + g];
;       float gv[4] = {bf2f(gg[0] & 0xffffu), bf2f(gg[0] >> 16), bf2f(gg[1] & 0xffffu), bf2f(gg[1] >> 16)};
;       float ov[4];
; #pragma unroll
;       for (int j = 0; j < 4; ++j) {
;         const float sg = gv[j] * __builtin_amdgcn_rcpf(1.f + __builtin_amdgcn_exp2f(-LOG2E * gv[j]));
;         ov[j] = o[cb][4 * g + j] * inv * sg;
;       }
;       *(unsigned*)((unsigned char*)yrow + dv) = pk4_fp8(ov[0] * Y_SCALE, ov[1] * Y_SCALE, ov[2] * Y_SCALE, ov[3] * Y_SCALE);
;       __builtin_amdgcn_sched_barrier(0);
;     }
	v_permlane32_swap_b32_e32 v72, v74
	v_permlane32_swap_b32_e32 v73, v75
	v_lshlrev_b32_e32 v18, 16, v74
	v_mul_f32_e32 v22, 0xbfb8aa3b, v18
	v_exp_f32_e32 v22, v22
	v_and_b32_e32 v19, 0xffff0000, v74
	v_lshlrev_b32_e32 v20, 16, v75
	v_and_b32_e32 v21, 0xffff0000, v75
	v_add_f32_e32 v22, 1.0, v22
	v_rcp_f32_e32 v22, v22
	s_nop 0
	v_mul_f32_e32 v18, v22, v18
	v_mul_f32_e32 v22, v30, v0
	v_mul_f32_e32 v18, v22, v18
	v_mul_f32_e32 v22, 0xbfb8aa3b, v19
	v_exp_f32_e32 v22, v22
	v_mul_f32_e32 v18, 0x41800000, v18
	v_med3_f32 v18, v18, s93, v223
	v_add_f32_e32 v22, 1.0, v22
	v_rcp_f32_e32 v22, v22
	s_nop 0
	v_mul_f32_e32 v19, v22, v19
	v_mul_f32_e32 v22, v31, v0
	v_mul_f32_e32 v19, v22, v19
	v_mul_f32_e32 v22, 0xbfb8aa3b, v20
	v_exp_f32_e32 v22, v22
	v_mul_f32_e32 v19, 0x41800000, v19
	v_med3_f32 v19, v19, s93, v223
	v_add_f32_e32 v22, 1.0, v22
	v_rcp_f32_e32 v22, v22
	s_nop 0
	v_mul_f32_e32 v20, v22, v20
	v_mul_f32_e32 v22, v32, v0
	v_mul_f32_e32 v20, v22, v20
	v_mul_f32_e32 v22, 0xbfb8aa3b, v21
	v_exp_f32_e32 v22, v22
	v_mul_f32_e32 v20, 0x41800000, v20
	v_add_f32_e32 v22, 1.0, v22
	v_rcp_f32_e32 v22, v22
	s_nop 0
	v_mul_f32_e32 v21, v22, v21
	v_mul_f32_e32 v22, v33, v0
	v_mul_f32_e32 v21, v22, v21
	v_mov_b32_e32 v215, v1
	v_cvt_pk_fp8_f32 v215, v18, v19
	v_mul_f32_e32 v21, 0x41800000, v21
	v_med3_f32 v18, v20, s93, v223
	v_med3_f32 v19, v21, s93, v223
	v_cvt_pk_fp8_f32 v215, v18, v19 op_sel:[0,0,1]
	s_nop 1
	v_permlane32_swap_b32_e32 v212, v213
	v_permlane32_swap_b32_e32 v214, v215
	global_store_dwordx4 v[216:217], v[212:215], off offset:2112
	s_waitcnt vmcnt(5)
	v_lshlrev_b32_e32 v18, 16, v72
	v_mul_f32_e32 v22, 0xbfb8aa3b, v18
	v_exp_f32_e32 v22, v22
	v_and_b32_e32 v19, 0xffff0000, v72
	v_mul_f32_e32 v2, v2, v0
	v_lshlrev_b32_e32 v20, 16, v73
	v_add_f32_e32 v22, 1.0, v22
	v_rcp_f32_e32 v22, v22
	v_mul_f32_e32 v3, v3, v0
	v_and_b32_e32 v21, 0xffff0000, v73
	v_mul_f32_e32 v4, v4, v0
	v_mul_f32_e32 v18, v22, v18
	v_mul_f32_e32 v2, v2, v18
	v_mul_f32_e32 v18, 0xbfb8aa3b, v19
	v_exp_f32_e32 v18, v18
	v_mul_f32_e32 v5, v5, v0
	v_mul_f32_e32 v2, 0x41800000, v2
	v_med3_f32 v2, v2, s93, v223
	v_add_f32_e32 v18, 1.0, v18
	v_rcp_f32_e32 v18, v18
	s_nop 0
	v_mul_f32_e32 v18, v18, v19
	v_mul_f32_e32 v3, v3, v18
	v_mul_f32_e32 v18, 0xbfb8aa3b, v20
	v_exp_f32_e32 v18, v18
	v_mul_f32_e32 v3, 0x41800000, v3
	v_med3_f32 v3, v3, s93, v223
	v_add_f32_e32 v18, 1.0, v18
	v_rcp_f32_e32 v18, v18
	s_nop 0
	v_mul_f32_e32 v18, v18, v20
	v_mul_f32_e32 v4, v4, v18
	v_mul_f32_e32 v18, 0xbfb8aa3b, v21
	v_exp_f32_e32 v18, v18
	v_mul_f32_e32 v4, 0x41800000, v4
	v_add_f32_e32 v18, 1.0, v18
	v_rcp_f32_e32 v18, v18
	s_nop 0
	v_mul_f32_e32 v18, v18, v21
	v_mul_f32_e32 v5, v5, v18
	v_mov_b32_e32 v212, v1
	v_cvt_pk_fp8_f32 v212, v2, v3
	v_mul_f32_e32 v5, 0x41800000, v5
	v_med3_f32 v2, v4, s93, v223
	v_med3_f32 v3, v5, s93, v223
	v_cvt_pk_fp8_f32 v212, v2, v3 op_sel:[0,0,1]
	s_waitcnt vmcnt(4)
	v_permlane32_swap_b32_e32 v68, v70
	v_permlane32_swap_b32_e32 v69, v71
	v_lshlrev_b32_e32 v2, 16, v70
	v_mul_f32_e32 v18, 0xbfb8aa3b, v2
	v_exp_f32_e32 v18, v18
	v_and_b32_e32 v3, 0xffff0000, v70
	v_mul_f32_e32 v6, v6, v0
	v_lshlrev_b32_e32 v4, 16, v71
	v_add_f32_e32 v18, 1.0, v18
	v_rcp_f32_e32 v18, v18
	v_and_b32_e32 v5, 0xffff0000, v71
	v_mul_f32_e32 v2, v18, v2
	v_mul_f32_e32 v2, v6, v2
	v_mul_f32_e32 v6, 0xbfb8aa3b, v3
	v_exp_f32_e32 v6, v6
	v_mul_f32_e32 v2, 0x41800000, v2
	v_med3_f32 v2, v2, s93, v223
	v_add_f32_e32 v6, 1.0, v6
	v_rcp_f32_e32 v6, v6
	s_nop 0
	v_mul_f32_e32 v3, v6, v3
	v_mul_f32_e32 v6, v7, v0
	v_mul_f32_e32 v3, v6, v3
	v_mul_f32_e32 v6, 0xbfb8aa3b, v4
	v_exp_f32_e32 v6, v6
	v_mul_f32_e32 v3, 0x41800000, v3
	v_med3_f32 v3, v3, s93, v223
	v_add_f32_e32 v6, 1.0, v6
	v_rcp_f32_e32 v6, v6
	s_nop 0
	v_mul_f32_e32 v4, v6, v4
	v_mul_f32_e32 v6, v8, v0
	v_mul_f32_e32 v4, v6, v4
	v_mul_f32_e32 v6, 0xbfb8aa3b, v5
	v_exp_f32_e32 v6, v6
	v_mul_f32_e32 v4, 0x41800000, v4
	v_add_f32_e32 v6, 1.0, v6
	v_rcp_f32_e32 v6, v6
	s_nop 0
	v_mul_f32_e32 v5, v6, v5
	v_mul_f32_e32 v6, v9, v0
	v_mul_f32_e32 v5, v6, v5
	v_mov_b32_e32 v214, v1
	v_cvt_pk_fp8_f32 v214, v2, v3
	v_mul_f32_e32 v5, 0x41800000, v5
	v_med3_f32 v2, v4, s93, v223
	v_med3_f32 v3, v5, s93, v223
	v_cvt_pk_fp8_f32 v214, v2, v3 op_sel:[0,0,1]
	s_waitcnt vmcnt(4)
	v_lshlrev_b32_e32 v2, 16, v68
	v_mul_f32_e32 v6, 0xbfb8aa3b, v2
	v_exp_f32_e32 v6, v6
	v_and_b32_e32 v3, 0xffff0000, v68
	v_lshlrev_b32_e32 v4, 16, v69
	v_and_b32_e32 v5, 0xffff0000, v69
	v_add_f32_e32 v6, 1.0, v6
	v_rcp_f32_e32 v6, v6
	s_nop 0
	v_mul_f32_e32 v2, v6, v2
	v_mul_f32_e32 v6, v10, v0
	v_mul_f32_e32 v2, v6, v2
	v_mul_f32_e32 v6, 0xbfb8aa3b, v3
	v_exp_f32_e32 v6, v6
	v_mul_f32_e32 v2, 0x41800000, v2
	v_med3_f32 v2, v2, s93, v223
	v_add_f32_e32 v6, 1.0, v6
	v_rcp_f32_e32 v6, v6
	s_nop 0
	v_mul_f32_e32 v3, v6, v3
	v_mul_f32_e32 v6, v11, v0
	v_mul_f32_e32 v3, v6, v3
	v_mul_f32_e32 v6, 0xbfb8aa3b, v4
	v_exp_f32_e32 v6, v6
	v_mul_f32_e32 v3, 0x41800000, v3
	v_med3_f32 v3, v3, s93, v223
	v_add_f32_e32 v6, 1.0, v6
	v_rcp_f32_e32 v6, v6
	s_nop 0
	v_mul_f32_e32 v4, v6, v4
	v_mul_f32_e32 v6, v12, v0
	v_mul_f32_e32 v4, v6, v4
	v_mul_f32_e32 v6, 0xbfb8aa3b, v5
	v_exp_f32_e32 v6, v6
	v_mul_f32_e32 v4, 0x41800000, v4
	v_add_f32_e32 v6, 1.0, v6
	v_rcp_f32_e32 v6, v6
	s_nop 0
	v_mul_f32_e32 v5, v6, v5
	v_mul_f32_e32 v6, v13, v0
	v_mul_f32_e32 v5, v6, v5
	v_mov_b32_e32 v213, v1
	v_cvt_pk_fp8_f32 v213, v2, v3
	v_mul_f32_e32 v5, 0x41800000, v5
	v_med3_f32 v2, v4, s93, v223
	v_med3_f32 v3, v5, s93, v223
	v_cvt_pk_fp8_f32 v213, v2, v3 op_sel:[0,0,1]
	s_waitcnt vmcnt(3)
	v_lshlrev_b32_e32 v2, 16, v66
	v_mul_f32_e32 v6, 0xbfb8aa3b, v2
	v_exp_f32_e32 v6, v6
	v_and_b32_e32 v3, 0xffff0000, v66
	v_lshlrev_b32_e32 v4, 16, v67
	v_and_b32_e32 v5, 0xffff0000, v67
	v_add_f32_e32 v6, 1.0, v6
	v_rcp_f32_e32 v6, v6
	s_nop 0
	v_mul_f32_e32 v2, v6, v2
	v_mul_f32_e32 v6, v14, v0
	v_mul_f32_e32 v2, v6, v2
	v_mul_f32_e32 v6, 0xbfb8aa3b, v3
	v_exp_f32_e32 v6, v6
	v_mul_f32_e32 v2, 0x41800000, v2
	v_med3_f32 v2, v2, s93, v223
	v_add_f32_e32 v6, 1.0, v6
	v_rcp_f32_e32 v6, v6
	s_nop 0
	v_mul_f32_e32 v3, v6, v3
	v_mul_f32_e32 v6, v15, v0
	v_mul_f32_e32 v3, v6, v3
	v_mul_f32_e32 v6, 0xbfb8aa3b, v4
	v_exp_f32_e32 v6, v6
	v_mul_f32_e32 v3, 0x41800000, v3
	v_med3_f32 v3, v3, s93, v223
	v_add_f32_e32 v6, 1.0, v6
	v_rcp_f32_e32 v6, v6
	s_nop 0
	v_mul_f32_e32 v4, v6, v4
	v_mul_f32_e32 v6, v16, v0
	v_mul_f32_e32 v4, v6, v4
	v_mul_f32_e32 v6, 0xbfb8aa3b, v5
	v_exp_f32_e32 v6, v6
	v_mul_f32_e32 v0, v17, v0
	v_mul_f32_e32 v4, 0x41800000, v4
	v_add_f32_e32 v6, 1.0, v6
	v_rcp_f32_e32 v6, v6
	s_nop 0
	v_mul_f32_e32 v5, v6, v5
	v_mul_f32_e32 v0, v0, v5
	v_mov_b32_e32 v215, v1
	v_cvt_pk_fp8_f32 v215, v2, v3
	v_mul_f32_e32 v0, 0x41800000, v0
	v_med3_f32 v2, v4, s93, v223
	v_med3_f32 v0, v0, s93, v223
	v_cvt_pk_fp8_f32 v215, v2, v0 op_sel:[0,0,1]
	s_nop 1
	v_permlane32_swap_b32_e32 v212, v213
	v_permlane32_swap_b32_e32 v214, v215
	global_store_dwordx4 v[216:217], v[212:215], off offset:2144
	s_branch .LBB0_1239

; template <int DQK, int W1, int DV, int VW, int MODE> ...
;     ...
;       {
;         f32x16 e0 = s[0], e1 = s[1];
;         if (MODE != 0) { const float nm = -m; e0 = e0 + nm; e1 = e1 + nm; }
; #pragma unroll
;         for (int i = 0; i < 16; ++i) { e0[i] = __builtin_amdgcn_exp2f(e0[i]); e1[i] = __builtin_amdgcn_exp2f(e1[i]); }
;         s[0] = e0; s[1] = e1;
;         const f32x16 sm = e0 + e1;
;         typedef __attribute__((ext_vector_type(8))) float f32x8;
;         const f32x8 h8 = sm.lo + sm.hi;
;         const f32x4 h4 = h8.lo + h8.hi;
;         const f32x2 h2 = h4.lo + h4.hi;
;         l += h2[0] + h2[1];
;       }
;       bf16x8 pb[2][2];
; #pragma unroll
;       for (int n = 0; n < 2; ++n)
; #pragma unroll
;         for (int s2 = 0; s2 < 2; ++s2) {
;           u32x4 pw = {pk2(s[n][8 * s2 + 0], s[n][8 * s2 + 1]), pk2(s[n][8 * s2 + 2], s[n][8 * s2 + 3]),
;                       pk2(s[n][8 * s2 + 4], s[n][8 * s2 + 5]), pk2(s[n][8 * s2 + 6], s[n][8 * s2 + 7])};
;           pb[n][s2] = __builtin_bit_cast(bf16x8, pw);
;         }
;       pv_block<0>(o[0], bufa + vlane, pb);
;       if constexpr (NCB > 1) pv_block<1>(o[1], bufa + vlane, pb);
;       if constexpr (NCB > 2) pv_block<2>(o[2], bufa + vlane, pb);
;       if constexpr (NCB > 3) pv_block<3>(o[3], bufa + vlane, pb);
.LBB0_1319:
	v_mov_b32_e32 v105, v104
	v_mov_b32_e32 v68, v104
	v_mov_b32_e32 v69, v104
	v_mov_b32_e32 v70, v104
	v_mov_b32_e32 v71, v104
	v_mov_b32_e32 v72, v104
	v_mov_b32_e32 v73, v104
	v_mov_b32_e32 v74, v104
	v_mov_b32_e32 v75, v104
	v_mov_b32_e32 v76, v104
	v_mov_b32_e32 v77, v104
	v_mov_b32_e32 v78, v104
	v_mov_b32_e32 v79, v104
	v_mov_b32_e32 v80, v104
	v_mov_b32_e32 v81, v104
	v_pk_add_f32 v[64:65], v[64:65], v[80:81]
	v_pk_add_f32 v[62:63], v[62:63], v[78:79]
	v_pk_add_f32 v[60:61], v[60:61], v[76:77]
	v_pk_add_f32 v[58:59], v[58:59], v[74:75]
	v_pk_add_f32 v[56:57], v[56:57], v[72:73]
	v_pk_add_f32 v[54:55], v[54:55], v[70:71]
	v_pk_add_f32 v[52:53], v[52:53], v[68:69]
	v_pk_add_f32 v[50:51], v[50:51], v[104:105]
	v_pk_add_f32 v[48:49], v[48:49], v[80:81]
	v_pk_add_f32 v[46:47], v[46:47], v[78:79]
	v_pk_add_f32 v[44:45], v[44:45], v[76:77]
	v_pk_add_f32 v[42:43], v[42:43], v[74:75]
	v_pk_add_f32 v[66:67], v[66:67], v[72:73]
	v_pk_add_f32 v[38:39], v[38:39], v[70:71]
	v_pk_add_f32 v[36:37], v[36:37], v[68:69]
	v_pk_add_f32 v[34:35], v[34:35], v[104:105]
	v_exp_f32_e32 v50, v50
	v_exp_f32_e32 v68, v34
	v_exp_f32_e32 v51, v51
	v_exp_f32_e32 v69, v35
	v_exp_f32_e32 v52, v52
	v_exp_f32_e32 v70, v36
	v_exp_f32_e32 v53, v53
	v_exp_f32_e32 v71, v37
	v_exp_f32_e32 v36, v54
	v_exp_f32_e32 v38, v38
	v_exp_f32_e32 v37, v55
	v_exp_f32_e32 v39, v39
	v_exp_f32_e32 v54, v56
	v_exp_f32_e32 v56, v66
	v_exp_f32_e32 v55, v57
	v_exp_f32_e32 v57, v67
	v_exp_f32_e32 v58, v58
	v_exp_f32_e32 v66, v42
	v_exp_f32_e32 v59, v59
	v_exp_f32_e32 v67, v43
	v_exp_f32_e32 v60, v60
	v_exp_f32_e32 v72, v44
	v_exp_f32_e32 v61, v61
	v_exp_f32_e32 v73, v45
	v_exp_f32_e32 v44, v62
	v_exp_f32_e32 v62, v46
	v_exp_f32_e32 v45, v63
	v_exp_f32_e32 v63, v47
	v_exp_f32_e32 v46, v64
	v_exp_f32_e32 v64, v48
	v_exp_f32_e32 v47, v65
	v_exp_f32_e32 v65, v49
	v_mov_b64_e32 v[40:41], s[82:83]
	v_mad_u64_u32 v[40:41], s[0:1], v86, s34, v[40:41]
	v_mad_i32_i24 v41, v87, s34, v41
	v_pk_add_f32 v[34:35], v[60:61], v[72:73]
	v_pk_add_f32 v[42:43], v[52:53], v[70:71]
	v_pk_add_f32 v[48:49], v[46:47], v[64:65]
	v_pk_add_f32 v[74:75], v[54:55], v[56:57]
	v_pk_add_f32 v[76:77], v[50:51], v[68:69]
	v_pk_add_f32 v[78:79], v[58:59], v[66:67]
	v_pk_add_f32 v[80:81], v[44:45], v[62:63]
	v_pk_add_f32 v[86:87], v[36:37], v[38:39]
	v_pk_add_f32 v[76:77], v[76:77], v[78:79]
	v_pk_add_f32 v[80:81], v[86:87], v[80:81]
	v_pk_add_f32 v[48:49], v[74:75], v[48:49]
	v_pk_add_f32 v[34:35], v[42:43], v[34:35]
	v_pk_add_f32 v[42:43], v[76:77], v[80:81]
	v_pk_add_f32 v[34:35], v[34:35], v[48:49]
	v_cvt_pk_bf16_f32 v36, v36, v37
	v_pk_add_f32 v[34:35], v[42:43], v[34:35]
	v_cvt_pk_bf16_f32 v37, v54, v55
	v_add_f32_e32 v74, v34, v35
	v_cvt_pk_bf16_f32 v34, v50, v51
	v_cvt_pk_bf16_f32 v35, v52, v53
	v_cvt_pk_bf16_f32 v42, v58, v59
	v_cvt_pk_bf16_f32 v43, v60, v61
	v_cvt_pk_bf16_f32 v44, v44, v45
	v_cvt_pk_bf16_f32 v45, v46, v47
	v_cvt_pk_bf16_f32 v46, v68, v69
	v_cvt_pk_bf16_f32 v49, v56, v57
	v_cvt_pk_bf16_f32 v50, v66, v67
	v_cvt_pk_bf16_f32 v52, v62, v63
	v_cvt_pk_bf16_f32 v53, v64, v65
	ds_read_b64_tr_b16 v[66:67], v101 offset:0
	ds_read_b64_tr_b16 v[68:69], v101 offset:0x200
	ds_read_b64_tr_b16 v[62:63], v101 offset:0x400
	ds_read_b64_tr_b16 v[64:65], v101 offset:0x600
	ds_read_b64_tr_b16 v[58:59], v101 offset:0x800
	ds_read_b64_tr_b16 v[60:61], v101 offset:0xa00
	ds_read_b64_tr_b16 v[54:55], v101 offset:0xc00
	ds_read_b64_tr_b16 v[56:57], v101 offset:0xe00
	s_waitcnt lgkmcnt(0)
	v_cvt_pk_bf16_f32 v47, v70, v71
	v_mfma_f32_32x32x16_bf16 v[18:33], v[66:69], v[34:37], v[18:33]
	v_cvt_pk_bf16_f32 v48, v38, v39
	v_cvt_pk_bf16_f32 v51, v72, v73
	v_add_f32_e32 v38, v106, v74
	s_mov_b64 s[0:1], 0x1c00
	v_lshl_add_u64 v[40:41], v[40:41], 0, s[18:19]
	v_mov_b32_e32 v83, v1
	v_mfma_f32_32x32x16_bf16 v[18:33], v[62:65], v[42:45], v[18:33]
	v_mfma_f32_32x32x16_bf16 v[18:33], v[58:61], v[46:49], v[18:33]
	v_mfma_f32_32x32x16_bf16 v[18:33], v[54:57], v[50:53], v[18:33]
	ds_read_b64_tr_b16 v[66:67], v101 offset:0x1000
	ds_read_b64_tr_b16 v[68:69], v101 offset:0x1200
	ds_read_b64_tr_b16 v[62:63], v101 offset:0x1400
	ds_read_b64_tr_b16 v[64:65], v101 offset:0x1600
	ds_read_b64_tr_b16 v[58:59], v101 offset:0x1800
	ds_read_b64_tr_b16 v[60:61], v101 offset:0x1a00
	ds_read_b64_tr_b16 v[54:55], v101 offset:0x1c00
	ds_read_b64_tr_b16 v[56:57], v101 offset:0x1e00
	s_waitcnt lgkmcnt(0)
	s_waitcnt vmcnt(0)
	s_barrier
; DI float bf2f(unsigned b) { return __uint_as_float(b << 16); }
; template <int DQK, int W1, int DV, int VW, int MODE> ...
;     ...
;       pv_block<0>(o[0], bufa + vlane, pb);
;       if constexpr (NCB > 1) pv_block<1>(o[1], bufa + vlane, pb);
;       if constexpr (NCB > 2) pv_block<2>(o[2], bufa + vlane, pb);
;       if constexpr (NCB > 3) pv_block<3>(o[3], bufa + vlane, pb);
;     }
;     asm volatile("s_waitcnt vmcnt(0)" ::: "memory");
;     __syncthreads();
;   }
;   const float inv = __builtin_amdgcn_rcpf(xhalf_sum(l));
;   u32x2 ggv[NCB * 4];
; #pragma unroll
;   for (int cb = 0; cb < NCB; ++cb)
; #pragma unroll
;     for (int g = 0; g < 4; ++g) ggv[cb * 4 + g] = *(const u32x2*)(grow + 32 * cb + 8 * g + 4 * hi);
;   __builtin_amdgcn_sched_barrier(0);
; #pragma unroll
;   for (int cb = 0; cb < NCB; ++cb)
; #pragma unroll
;     for (int g = 0; g < 4; ++g) {
;       const int dv = 32 * cb + 8 * g + 4 * hi;
;       const u32x2 gg = ggv[cb * 4 + g];
;       float gv[4] = {bf2f(gg[0] & 0xffffu), bf2f(gg[0] >> 16), bf2f(gg[1] & 0xffffu), bf2f(gg[1] >> 16)};
;       float ov[4];
; #pragma unroll
;       for (int j = 0; j < 4; ++j) {
;         const float sg = gv[j] * __builtin_amdgcn_rcpf(1.f + __builtin_amdgcn_exp2f(-LOG2E * gv[j]));
;         ov[j] = o[cb][4 * g + j] * inv * sg;
;       }
;       *(unsigned*)((unsigned char*)yrow + dv) = pk4_fp8(ov[0] * Y_SCALE, ov[1] * Y_SCALE, ov[2] * Y_SCALE, ov[3] * Y_SCALE);
;       __builtin_amdgcn_sched_barrier(0);
;     }
	v_mfma_f32_32x32x16_bf16 v[2:17], v[66:69], v[34:37], v[2:17]
	v_mov_b32_e32 v34, v38
	s_nop 1
	v_permlane32_swap_b32_e32 v38, v34
	v_mov_b32_e32 v35, v1
	v_mfma_f32_32x32x16_bf16 v[2:17], v[62:65], v[42:45], v[2:17]
	v_mfma_f32_32x32x16_bf16 v[2:17], v[58:61], v[46:49], v[2:17]
	v_mfma_f32_32x32x16_bf16 v[2:17], v[54:57], v[50:53], v[2:17]
	v_add_f32_e32 v54, v38, v34
	v_lshlrev_b32_e32 v34, 1, v82
	v_lshl_add_u64 v[34:35], v[84:85], 0, v[34:35]
	v_lshl_add_u64 v[50:51], v[34:35], 0, s[0:1]
	s_movk_i32 s0, 0x1000
	v_add_co_u32_e32 v34, vcc, s0, v34
	s_nop 1
	v_addc_co_u32_e32 v35, vcc, 0, v35, vcc
	v_bfe_i32 v211, v179, 5, 1
	v_mul_i32_i24_e32 v210, 24, v211
	v_lshl_add_u64 v[208:209], v[50:51], 0, v[210:211]
	global_load_dwordx2 v[52:53], v[34:35], off offset:3072
	global_load_dwordx4 v[46:49], v[208:209], off offset:32
	global_load_dwordx4 v[42:45], v[208:209], off offset:64
	global_load_dwordx4 v[36:39], v[208:209], off offset:96
	global_load_dwordx2 v[34:35], v[50:51], off offset:112
	v_rcp_f32_e32 v50, v54
	s_waitcnt vmcnt(4)
	v_lshlrev_b32_e32 v51, 16, v52
	v_mul_f32_e32 v55, 0xbfb8aa3b, v51
	v_exp_f32_e32 v55, v55
	v_and_b32_e32 v52, 0xffff0000, v52
	v_mul_f32_e32 v18, v18, v50
	v_lshlrev_b32_e32 v54, 16, v53
	v_add_f32_e32 v55, 1.0, v55
	v_rcp_f32_e32 v55, v55
	v_mul_f32_e32 v19, v19, v50
	v_and_b32_e32 v53, 0xffff0000, v53
	v_mul_f32_e32 v20, v20, v50
	v_mul_f32_e32 v51, v55, v51
	v_mul_f32_e32 v18, v18, v51
	v_mul_f32_e32 v51, 0xbfb8aa3b, v52
	v_exp_f32_e32 v51, v51
	v_mul_f32_e32 v21, v21, v50
	v_mul_f32_e32 v18, 0x41800000, v18
	v_med3_f32 v18, v18, s93, v223
	v_add_f32_e32 v51, 1.0, v51
	v_rcp_f32_e32 v51, v51
	s_nop 0
	v_mul_f32_e32 v51, v51, v52
	v_mul_f32_e32 v19, v19, v51
	v_mul_f32_e32 v51, 0xbfb8aa3b, v54
	v_exp_f32_e32 v51, v51
	v_mul_f32_e32 v19, 0x41800000, v19
	v_med3_f32 v19, v19, s93, v223
	v_add_f32_e32 v51, 1.0, v51
	v_rcp_f32_e32 v51, v51
	s_nop 0
	v_mul_f32_e32 v51, v51, v54
	v_mul_f32_e32 v20, v20, v51
	v_mul_f32_e32 v51, 0xbfb8aa3b, v53
	v_exp_f32_e32 v51, v51
	v_mul_f32_e32 v20, 0x41800000, v20
	v_add_f32_e32 v51, 1.0, v51
	v_rcp_f32_e32 v51, v51
	s_nop 0
	v_mul_f32_e32 v51, v51, v53
	v_mul_f32_e32 v21, v21, v51
	v_mov_b32_e32 v212, v1
	v_cvt_pk_fp8_f32 v212, v18, v19
	v_mul_f32_e32 v21, 0x41800000, v21
	v_med3_f32 v18, v20, s93, v223
	v_med3_f32 v19, v21, s93, v223
	v_cvt_pk_fp8_f32 v212, v18, v19 op_sel:[0,0,1]
	v_lshl_add_u64 v[18:19], v[40:41], 0, v[82:83]
	s_waitcnt vmcnt(3)
	v_permlane32_swap_b32_e32 v46, v48
	v_permlane32_swap_b32_e32 v47, v49
	v_lshlrev_b32_e32 v20, 16, v48
	v_and_b32_e32 v21, 0xffff0000, v48
	v_mul_f32_e32 v48, 0xbfb8aa3b, v20
	v_exp_f32_e32 v48, v48
	v_mul_f32_e32 v22, v22, v50
	v_lshlrev_b32_e32 v40, 16, v49
	v_and_b32_e32 v41, 0xffff0000, v49
	v_add_f32_e32 v48, 1.0, v48
	v_rcp_f32_e32 v48, v48
	s_nop 0
	v_mul_f32_e32 v20, v48, v20
	v_mul_f32_e32 v20, v22, v20
	v_mul_f32_e32 v22, 0xbfb8aa3b, v21
	v_exp_f32_e32 v22, v22
	v_mul_f32_e32 v20, 0x41800000, v20
	v_med3_f32 v20, v20, s93, v223
	v_add_f32_e32 v22, 1.0, v22
	v_rcp_f32_e32 v22, v22
	s_nop 0
	v_mul_f32_e32 v21, v22, v21
	v_mul_f32_e32 v22, v23, v50
	v_mul_f32_e32 v21, v22, v21
	v_mul_f32_e32 v22, 0xbfb8aa3b, v40
	v_exp_f32_e32 v22, v22
	v_mul_f32_e32 v23, v24, v50
	v_mul_f32_e32 v24, v25, v50
	v_mul_f32_e32 v21, 0x41800000, v21
	v_add_f32_e32 v22, 1.0, v22
	v_rcp_f32_e32 v22, v22
	v_med3_f32 v21, v21, s93, v223
	v_mul_f32_e32 v22, v22, v40
	v_mul_f32_e32 v22, v23, v22
	v_mul_f32_e32 v23, 0xbfb8aa3b, v41
	v_exp_f32_e32 v23, v23
	v_mul_f32_e32 v22, 0x41800000, v22
	v_add_f32_e32 v23, 1.0, v23
	v_rcp_f32_e32 v23, v23
	s_nop 0
	v_mul_f32_e32 v23, v23, v41
	v_mul_f32_e32 v23, v24, v23
	v_mov_b32_e32 v214, v1
	v_cvt_pk_fp8_f32 v214, v20, v21
	v_mul_f32_e32 v23, 0x41800000, v23
	v_med3_f32 v20, v22, s93, v223
	v_med3_f32 v21, v23, s93, v223
	v_cvt_pk_fp8_f32 v214, v20, v21 op_sel:[0,0,1]
	s_waitcnt vmcnt(3)
	v_lshlrev_b32_e32 v20, 16, v46
	v_mul_f32_e32 v24, 0xbfb8aa3b, v20
	v_exp_f32_e32 v24, v24
	v_and_b32_e32 v21, 0xffff0000, v46
	v_lshlrev_b32_e32 v22, 16, v47
	v_and_b32_e32 v23, 0xffff0000, v47
	v_add_f32_e32 v24, 1.0, v24
	v_rcp_f32_e32 v24, v24
	s_nop 0
	v_mul_f32_e32 v20, v24, v20
	v_mul_f32_e32 v24, v26, v50
	v_mul_f32_e32 v20, v24, v20
	v_mul_f32_e32 v24, 0xbfb8aa3b, v21
	v_exp_f32_e32 v24, v24
	v_mul_f32_e32 v20, 0x41800000, v20
	v_med3_f32 v20, v20, s93, v223
	v_add_f32_e32 v24, 1.0, v24
	v_rcp_f32_e32 v24, v24
	s_nop 0
	v_mul_f32_e32 v21, v24, v21
	v_mul_f32_e32 v24, v27, v50
	v_mul_f32_e32 v21, v24, v21
	v_mul_f32_e32 v24, 0xbfb8aa3b, v22
	v_exp_f32_e32 v24, v24
	v_mul_f32_e32 v21, 0x41800000, v21
	v_med3_f32 v21, v21, s93, v223
	v_add_f32_e32 v24, 1.0, v24
	v_rcp_f32_e32 v24, v24
	s_nop 0
	v_mul_f32_e32 v22, v24, v22
	v_mul_f32_e32 v24, v28, v50
	v_mul_f32_e32 v22, v24, v22
	v_mul_f32_e32 v24, 0xbfb8aa3b, v23
	v_exp_f32_e32 v24, v24
	v_mul_f32_e32 v22, 0x41800000, v22
	v_add_f32_e32 v24, 1.0, v24
	v_rcp_f32_e32 v24, v24
	s_nop 0
	v_mul_f32_e32 v23, v24, v23
	v_mul_f32_e32 v24, v29, v50
	v_mul_f32_e32 v23, v24, v23
	v_mov_b32_e32 v213, v1
	v_cvt_pk_fp8_f32 v213, v20, v21
	v_mul_f32_e32 v23, 0x41800000, v23
	v_med3_f32 v20, v22, s93, v223
	v_med3_f32 v21, v23, s93, v223
	v_cvt_pk_fp8_f32 v213, v20, v21 op_sel:[0,0,1]
	s_waitcnt vmcnt(2)
; DI float bf2f(unsigned b) { return __uint_as_float(b << 16); }
; template <int DQK, int W1, int DV, int VW, int MODE> ...
;     ...
; #pragma unroll
;   for (int cb = 0; cb < NCB; ++cb)
; #pragma unroll
;     for (int g = 0; g < 4; ++g) {
;       const int dv = 32 * cb + 8 * g + 4 * hi;
;       const u32x2 gg = ggv[cb * 4 + g];
;       float gv[4] = {bf2f(gg[0] & 0xffffu), bf2f(gg[0] >> 16), bf2f(gg[1] & 0xffffu), bf2f(gg[1] >> 16)};
;       float ov[4];
; #pragma unroll
;       for (int j = 0; j < 4; ++j) {
;         const float sg = gv[j] * __builtin_amdgcn_rcpf(1.f + __builtin_amdgcn_exp2f(-LOG2E * gv[j]));
;         ov[j] = o[cb][4 * g + j] * inv * sg;
;       }
;       *(unsigned*)((unsigned char*)yrow + dv) = pk4_fp8(ov[0] * Y_SCALE, ov[1] * Y_SCALE, ov[2] * Y_SCALE, ov[3] * Y_SCALE);
;       __builtin_amdgcn_sched_barrier(0);
;     }
	v_permlane32_swap_b32_e32 v42, v44
	v_permlane32_swap_b32_e32 v43, v45
	v_lshlrev_b32_e32 v20, 16, v44
	v_mul_f32_e32 v24, 0xbfb8aa3b, v20
	v_exp_f32_e32 v24, v24
	v_and_b32_e32 v21, 0xffff0000, v44
	v_lshlrev_b32_e32 v22, 16, v45
	v_and_b32_e32 v23, 0xffff0000, v45
	v_add_f32_e32 v24, 1.0, v24
	v_rcp_f32_e32 v24, v24
	s_nop 0
	v_mul_f32_e32 v20, v24, v20
	v_mul_f32_e32 v24, v30, v50
	v_mul_f32_e32 v20, v24, v20
	v_mul_f32_e32 v24, 0xbfb8aa3b, v21
	v_exp_f32_e32 v24, v24
	v_mul_f32_e32 v20, 0x41800000, v20
	v_med3_f32 v20, v20, s93, v223
	v_add_f32_e32 v24, 1.0, v24
	v_rcp_f32_e32 v24, v24
	s_nop 0
	v_mul_f32_e32 v21, v24, v21
	v_mul_f32_e32 v24, v31, v50
	v_mul_f32_e32 v21, v24, v21
	v_mul_f32_e32 v24, 0xbfb8aa3b, v22
	v_exp_f32_e32 v24, v24
	v_mul_f32_e32 v21, 0x41800000, v21
	v_med3_f32 v21, v21, s93, v223
	v_add_f32_e32 v24, 1.0, v24
	v_rcp_f32_e32 v24, v24
	s_nop 0
	v_mul_f32_e32 v22, v24, v22
	v_mul_f32_e32 v24, v32, v50
	v_mul_f32_e32 v22, v24, v22
	v_mul_f32_e32 v24, 0xbfb8aa3b, v23
	v_exp_f32_e32 v24, v24
	v_mul_f32_e32 v22, 0x41800000, v22
	v_add_f32_e32 v24, 1.0, v24
	v_rcp_f32_e32 v24, v24
	s_nop 0
	v_mul_f32_e32 v23, v24, v23
	v_mul_f32_e32 v24, v33, v50
	v_mul_f32_e32 v23, v24, v23
	v_mov_b32_e32 v215, v1
	v_cvt_pk_fp8_f32 v215, v20, v21
	v_mul_f32_e32 v23, 0x41800000, v23
	v_med3_f32 v20, v22, s93, v223
	v_med3_f32 v21, v23, s93, v223
	v_cvt_pk_fp8_f32 v215, v20, v21 op_sel:[0,0,1]
	v_and_b32_e32 v242, 32, v179
	v_lshrrev_b32_e32 v242, 3, v242
	v_lshl_add_u32 v242, v242, 1, v242
	v_mov_b32_e32 v243, 0
	v_lshl_add_u64 v[216:217], v[18:19], 0, v[242:243]
	s_nop 1
	v_permlane32_swap_b32_e32 v212, v213
	v_permlane32_swap_b32_e32 v214, v215
	global_store_dwordx4 v[216:217], v[212:215], off
	s_waitcnt vmcnt(3)
	v_lshlrev_b32_e32 v20, 16, v42
	v_mul_f32_e32 v24, 0xbfb8aa3b, v20
	v_exp_f32_e32 v24, v24
	v_and_b32_e32 v21, 0xffff0000, v42
	v_mul_f32_e32 v2, v2, v50
	v_lshlrev_b32_e32 v22, 16, v43
	v_add_f32_e32 v24, 1.0, v24
	v_rcp_f32_e32 v24, v24
	v_mul_f32_e32 v3, v3, v50
	v_and_b32_e32 v23, 0xffff0000, v43
	v_mul_f32_e32 v4, v4, v50
	v_mul_f32_e32 v20, v24, v20
	v_mul_f32_e32 v2, v2, v20
	v_mul_f32_e32 v20, 0xbfb8aa3b, v21
	v_exp_f32_e32 v20, v20
	v_mul_f32_e32 v5, v5, v50
	v_mul_f32_e32 v2, 0x41800000, v2
	v_med3_f32 v2, v2, s93, v223
	v_add_f32_e32 v20, 1.0, v20
	v_rcp_f32_e32 v20, v20
	s_nop 0
	v_mul_f32_e32 v20, v20, v21
	v_mul_f32_e32 v3, v3, v20
	v_mul_f32_e32 v20, 0xbfb8aa3b, v22
	v_exp_f32_e32 v20, v20
	v_mul_f32_e32 v3, 0x41800000, v3
	v_med3_f32 v3, v3, s93, v223
	v_add_f32_e32 v20, 1.0, v20
	v_rcp_f32_e32 v20, v20
	s_nop 0
	v_mul_f32_e32 v20, v20, v22
	v_mul_f32_e32 v4, v4, v20
	v_mul_f32_e32 v20, 0xbfb8aa3b, v23
	v_exp_f32_e32 v20, v20
	v_mul_f32_e32 v4, 0x41800000, v4
	v_add_f32_e32 v20, 1.0, v20
	v_rcp_f32_e32 v20, v20
	s_nop 0
	v_mul_f32_e32 v20, v20, v23
	v_mul_f32_e32 v5, v5, v20
	v_mov_b32_e32 v212, v1
	v_cvt_pk_fp8_f32 v212, v2, v3
	v_mul_f32_e32 v5, 0x41800000, v5
	v_med3_f32 v2, v4, s93, v223
	v_med3_f32 v3, v5, s93, v223
	v_cvt_pk_fp8_f32 v212, v2, v3 op_sel:[0,0,1]
	s_waitcnt vmcnt(2)
; DI float bf2f(unsigned b) { return __uint_as_float(b << 16); }
; template <int DQK, int W1, int DV, int VW, int MODE> ...
;     ...
; #pragma unroll
;   for (int cb = 0; cb < NCB; ++cb)
; #pragma unroll
;     for (int g = 0; g < 4; ++g) {
;       const int dv = 32 * cb + 8 * g + 4 * hi;
;       const u32x2 gg = ggv[cb * 4 + g];
;       float gv[4] = {bf2f(gg[0] & 0xffffu), bf2f(gg[0] >> 16), bf2f(gg[1] & 0xffffu), bf2f(gg[1] >> 16)};
;       float ov[4];
; #pragma unroll
;       for (int j = 0; j < 4; ++j) {
;         const float sg = gv[j] * __builtin_amdgcn_rcpf(1.f + __builtin_amdgcn_exp2f(-LOG2E * gv[j]));
;         ov[j] = o[cb][4 * g + j] * inv * sg;
;       }
;       *(unsigned*)((unsigned char*)yrow + dv) = pk4_fp8(ov[0] * Y_SCALE, ov[1] * Y_SCALE, ov[2] * Y_SCALE, ov[3] * Y_SCALE);
;       __builtin_amdgcn_sched_barrier(0);
;     }
	v_permlane32_swap_b32_e32 v36, v38
	v_permlane32_swap_b32_e32 v37, v39
	v_lshlrev_b32_e32 v2, 16, v38
	v_mul_f32_e32 v20, 0xbfb8aa3b, v2
	v_exp_f32_e32 v20, v20
	v_and_b32_e32 v3, 0xffff0000, v38
	v_mul_f32_e32 v6, v6, v50
	v_lshlrev_b32_e32 v4, 16, v39
	v_add_f32_e32 v20, 1.0, v20
	v_rcp_f32_e32 v20, v20
	v_and_b32_e32 v5, 0xffff0000, v39
	v_mul_f32_e32 v2, v20, v2
	v_mul_f32_e32 v2, v6, v2
	v_mul_f32_e32 v6, 0xbfb8aa3b, v3
	v_exp_f32_e32 v6, v6
	v_mul_f32_e32 v2, 0x41800000, v2
	v_med3_f32 v2, v2, s93, v223
	v_add_f32_e32 v6, 1.0, v6
	v_rcp_f32_e32 v6, v6
	s_nop 0
	v_mul_f32_e32 v3, v6, v3
	v_mul_f32_e32 v6, v7, v50
	v_mul_f32_e32 v3, v6, v3
	v_mul_f32_e32 v6, 0xbfb8aa3b, v4
	v_exp_f32_e32 v6, v6
	v_mul_f32_e32 v3, 0x41800000, v3
	v_med3_f32 v3, v3, s93, v223
	v_add_f32_e32 v6, 1.0, v6
	v_rcp_f32_e32 v6, v6
	s_nop 0
	v_mul_f32_e32 v4, v6, v4
	v_mul_f32_e32 v6, v8, v50
	v_mul_f32_e32 v4, v6, v4
	v_mul_f32_e32 v6, 0xbfb8aa3b, v5
	v_exp_f32_e32 v6, v6
	v_mul_f32_e32 v4, 0x41800000, v4
	v_add_f32_e32 v6, 1.0, v6
	v_rcp_f32_e32 v6, v6
	s_nop 0
	v_mul_f32_e32 v5, v6, v5
	v_mul_f32_e32 v6, v9, v50
	v_mul_f32_e32 v5, v6, v5
	v_mov_b32_e32 v214, v1
	v_cvt_pk_fp8_f32 v214, v2, v3
	v_mul_f32_e32 v5, 0x41800000, v5
	v_med3_f32 v2, v4, s93, v223
	v_med3_f32 v3, v5, s93, v223
	v_cvt_pk_fp8_f32 v214, v2, v3 op_sel:[0,0,1]
	s_waitcnt vmcnt(2)
	v_lshlrev_b32_e32 v2, 16, v36
	v_mul_f32_e32 v6, 0xbfb8aa3b, v2
	v_exp_f32_e32 v6, v6
	v_and_b32_e32 v3, 0xffff0000, v36
	v_lshlrev_b32_e32 v4, 16, v37
	v_and_b32_e32 v5, 0xffff0000, v37
	v_add_f32_e32 v6, 1.0, v6
	v_rcp_f32_e32 v6, v6
	s_nop 0
	v_mul_f32_e32 v2, v6, v2
	v_mul_f32_e32 v6, v10, v50
	v_mul_f32_e32 v2, v6, v2
	v_mul_f32_e32 v6, 0xbfb8aa3b, v3
	v_exp_f32_e32 v6, v6
	v_mul_f32_e32 v2, 0x41800000, v2
	v_med3_f32 v2, v2, s93, v223
	v_add_f32_e32 v6, 1.0, v6
	v_rcp_f32_e32 v6, v6
	s_nop 0
	v_mul_f32_e32 v3, v6, v3
	v_mul_f32_e32 v6, v11, v50
	v_mul_f32_e32 v3, v6, v3
	v_mul_f32_e32 v6, 0xbfb8aa3b, v4
	v_exp_f32_e32 v6, v6
	v_mul_f32_e32 v3, 0x41800000, v3
	v_med3_f32 v3, v3, s93, v223
	v_add_f32_e32 v6, 1.0, v6
	v_rcp_f32_e32 v6, v6
	s_nop 0
	v_mul_f32_e32 v4, v6, v4
	v_mul_f32_e32 v6, v12, v50
	v_mul_f32_e32 v4, v6, v4
	v_mul_f32_e32 v6, 0xbfb8aa3b, v5
	v_exp_f32_e32 v6, v6
	v_mul_f32_e32 v4, 0x41800000, v4
	v_add_f32_e32 v6, 1.0, v6
	v_rcp_f32_e32 v6, v6
	s_nop 0
	v_mul_f32_e32 v5, v6, v5
	v_mul_f32_e32 v6, v13, v50
	v_mul_f32_e32 v5, v6, v5
	v_mov_b32_e32 v213, v1
	v_cvt_pk_fp8_f32 v213, v2, v3
	v_mul_f32_e32 v5, 0x41800000, v5
	v_med3_f32 v2, v4, s93, v223
	v_med3_f32 v3, v5, s93, v223
	v_cvt_pk_fp8_f32 v213, v2, v3 op_sel:[0,0,1]
	s_waitcnt vmcnt(1)
	v_lshlrev_b32_e32 v2, 16, v34
	v_mul_f32_e32 v6, 0xbfb8aa3b, v2
	v_exp_f32_e32 v6, v6
	v_and_b32_e32 v3, 0xffff0000, v34
	v_lshlrev_b32_e32 v4, 16, v35
	v_and_b32_e32 v5, 0xffff0000, v35
	v_add_f32_e32 v6, 1.0, v6
	v_rcp_f32_e32 v6, v6
	s_nop 0
	v_mul_f32_e32 v2, v6, v2
	v_mul_f32_e32 v6, v14, v50
	v_mul_f32_e32 v2, v6, v2
	v_mul_f32_e32 v6, 0xbfb8aa3b, v3
	v_exp_f32_e32 v6, v6
	v_mul_f32_e32 v2, 0x41800000, v2
	v_med3_f32 v2, v2, s93, v223
	v_add_f32_e32 v6, 1.0, v6
	v_rcp_f32_e32 v6, v6
	s_nop 0
	v_mul_f32_e32 v3, v6, v3
	v_mul_f32_e32 v6, v15, v50
	v_mul_f32_e32 v3, v6, v3
	v_mul_f32_e32 v6, 0xbfb8aa3b, v4
	v_exp_f32_e32 v6, v6
	v_mul_f32_e32 v3, 0x41800000, v3
	v_med3_f32 v3, v3, s93, v223
	v_add_f32_e32 v6, 1.0, v6
	v_rcp_f32_e32 v6, v6
	s_nop 0
	v_mul_f32_e32 v4, v6, v4
	v_mul_f32_e32 v6, v16, v50
	v_mul_f32_e32 v4, v6, v4
	v_mul_f32_e32 v6, 0xbfb8aa3b, v5
	v_exp_f32_e32 v6, v6
	v_mul_f32_e32 v4, 0x41800000, v4
	v_add_f32_e32 v6, 1.0, v6
	v_rcp_f32_e32 v6, v6
	s_nop 0
	v_mul_f32_e32 v5, v6, v5
	v_mul_f32_e32 v6, v17, v50
	v_mul_f32_e32 v5, v6, v5
	v_mov_b32_e32 v215, v1
	v_cvt_pk_fp8_f32 v215, v2, v3
	v_mul_f32_e32 v5, 0x41800000, v5
	v_med3_f32 v2, v4, s93, v223
	v_med3_f32 v3, v5, s93, v223
	v_cvt_pk_fp8_f32 v215, v2, v3 op_sel:[0,0,1]
	s_nop 1
	v_permlane32_swap_b32_e32 v212, v213
	v_permlane32_swap_b32_e32 v214, v215
	global_store_dwordx4 v[216:217], v[212:215], off offset:32
	s_mov_b64 s[0:1], 0

; DI float bf2f(unsigned b) { return __uint_as_float(b << 16); }
; template <int DQK, int W1, int DV, int VW, int MODE> ...
;     ...
;   const float inv = __builtin_amdgcn_rcpf(xhalf_sum(l));
;   u32x2 ggv[NCB * 4];
; #pragma unroll
;   for (int cb = 0; cb < NCB; ++cb)
; #pragma unroll
;     for (int g = 0; g < 4; ++g) ggv[cb * 4 + g] = *(const u32x2*)(grow + 32 * cb + 8 * g + 4 * hi);
;   __builtin_amdgcn_sched_barrier(0);
; #pragma unroll
;   for (int cb = 0; cb < NCB; ++cb)
; #pragma unroll
;     for (int g = 0; g < 4; ++g) {
;       const int dv = 32 * cb + 8 * g + 4 * hi;
;       const u32x2 gg = ggv[cb * 4 + g];
;       float gv[4] = {bf2f(gg[0] & 0xffffu), bf2f(gg[0] >> 16), bf2f(gg[1] & 0xffffu), bf2f(gg[1] >> 16)};
;       float ov[4];
; #pragma unroll
;       for (int j = 0; j < 4; ++j) {
;         const float sg = gv[j] * __builtin_amdgcn_rcpf(1.f + __builtin_amdgcn_exp2f(-LOG2E * gv[j]));
;         ov[j] = o[cb][4 * g + j] * inv * sg;
;       }
;       *(unsigned*)((unsigned char*)yrow + dv) = pk4_fp8(ov[0] * Y_SCALE, ov[1] * Y_SCALE, ov[2] * Y_SCALE, ov[3] * Y_SCALE);
;       __builtin_amdgcn_sched_barrier(0);
;     }
.LBB0_1348:
	v_mov_b64_e32 v[34:35], s[82:83]
	v_mov_b32_e32 v0, v119
	v_mad_u64_u32 v[34:35], s[0:1], v86, s34, v[34:35]
	s_nop 0
	v_permlane32_swap_b32_e32 v119, v0
	v_mad_i32_i24 v35, v87, s34, v35
	v_add_f32_e32 v54, v119, v0
	v_lshlrev_b32_e32 v0, 1, v82
	v_lshl_add_u64 v[46:47], v[34:35], 0, s[10:11]
	v_lshl_add_u64 v[34:35], v[84:85], 0, v[0:1]
	s_mov_b64 s[0:1], 0x24a0
	v_lshl_add_u64 v[48:49], v[34:35], 0, s[0:1]
	s_movk_i32 s0, 0x2000
	v_add_co_u32_e32 v34, vcc, s0, v34
	v_mov_b32_e32 v83, v1
	s_nop 0
	v_addc_co_u32_e32 v35, vcc, 0, v35, vcc
	v_bfe_i32 v211, v179, 5, 1
	v_mul_i32_i24_e32 v210, 24, v211
	v_lshl_add_u64 v[208:209], v[48:49], 0, v[210:211]
	global_load_dwordx2 v[50:51], v[34:35], off offset:1184
	global_load_dwordx2 v[52:53], v[48:49], off offset:16
	global_load_dwordx4 v[42:45], v[208:209], off offset:48
	global_load_dwordx4 v[38:41], v[208:209], off offset:80
	global_load_dwordx4 v[34:37], v[208:209], off offset:112
	v_rcp_f32_e32 v0, v54
	s_waitcnt vmcnt(4)
	v_lshlrev_b32_e32 v48, 16, v50
	v_mul_f32_e32 v54, 0xbfb8aa3b, v48
	v_exp_f32_e32 v54, v54
	v_and_b32_e32 v49, 0xffff0000, v50
	v_mul_f32_e32 v18, v18, v0
	v_lshlrev_b32_e32 v50, 16, v51
	v_add_f32_e32 v54, 1.0, v54
	v_rcp_f32_e32 v54, v54
	v_mul_f32_e32 v19, v19, v0
	v_and_b32_e32 v51, 0xffff0000, v51
	v_mul_f32_e32 v20, v20, v0
	v_mul_f32_e32 v48, v54, v48
	v_mul_f32_e32 v18, v18, v48
	v_mul_f32_e32 v48, 0xbfb8aa3b, v49
	v_exp_f32_e32 v48, v48
	v_mul_f32_e32 v21, v21, v0
	v_mul_f32_e32 v18, 0x41800000, v18
	v_med3_f32 v18, v18, s93, v223
	v_add_f32_e32 v48, 1.0, v48
	v_rcp_f32_e32 v48, v48
	s_nop 0
	v_mul_f32_e32 v48, v48, v49
	v_mul_f32_e32 v19, v19, v48
	v_mul_f32_e32 v48, 0xbfb8aa3b, v50
	v_exp_f32_e32 v48, v48
	v_mul_f32_e32 v19, 0x41800000, v19
	v_med3_f32 v19, v19, s93, v223
	v_add_f32_e32 v48, 1.0, v48
	v_rcp_f32_e32 v48, v48
	s_nop 0
	v_mul_f32_e32 v48, v48, v50
	v_mul_f32_e32 v20, v20, v48
	v_mul_f32_e32 v48, 0xbfb8aa3b, v51
	v_exp_f32_e32 v48, v48
	v_mul_f32_e32 v20, 0x41800000, v20
	v_add_f32_e32 v48, 1.0, v48
	v_rcp_f32_e32 v48, v48
	s_nop 0
	v_mul_f32_e32 v48, v48, v51
	v_mul_f32_e32 v21, v21, v48
	v_mov_b32_e32 v212, v1
	v_cvt_pk_fp8_f32 v212, v18, v19
	v_mul_f32_e32 v21, 0x41800000, v21
	v_med3_f32 v18, v20, s93, v223
	v_med3_f32 v19, v21, s93, v223
	v_cvt_pk_fp8_f32 v212, v18, v19 op_sel:[0,0,1]
	v_lshl_add_u64 v[18:19], v[46:47], 0, v[82:83]
	s_waitcnt vmcnt(3)
	v_lshlrev_b32_e32 v20, 16, v52
	v_mul_f32_e32 v48, 0xbfb8aa3b, v20
	v_exp_f32_e32 v48, v48
	v_and_b32_e32 v21, 0xffff0000, v52
	v_mul_f32_e32 v22, v22, v0
	v_lshlrev_b32_e32 v46, 16, v53
	v_add_f32_e32 v48, 1.0, v48
	v_rcp_f32_e32 v48, v48
	v_and_b32_e32 v47, 0xffff0000, v53
	v_mul_f32_e32 v20, v48, v20
	v_mul_f32_e32 v20, v22, v20
	v_mul_f32_e32 v22, 0xbfb8aa3b, v21
	v_exp_f32_e32 v22, v22
	v_mul_f32_e32 v20, 0x41800000, v20
	v_med3_f32 v20, v20, s93, v223
	v_add_f32_e32 v22, 1.0, v22
	v_rcp_f32_e32 v22, v22
	s_nop 0
	v_mul_f32_e32 v21, v22, v21
	v_mul_f32_e32 v22, v23, v0
	v_mul_f32_e32 v21, v22, v21
	v_mul_f32_e32 v22, 0xbfb8aa3b, v46
	v_exp_f32_e32 v22, v22
	v_mul_f32_e32 v23, v24, v0
	v_mul_f32_e32 v24, v25, v0
	v_mul_f32_e32 v21, 0x41800000, v21
	v_add_f32_e32 v22, 1.0, v22
	v_rcp_f32_e32 v22, v22
	v_med3_f32 v21, v21, s93, v223
	v_mul_f32_e32 v22, v22, v46
	v_mul_f32_e32 v22, v23, v22
	v_mul_f32_e32 v23, 0xbfb8aa3b, v47
	v_exp_f32_e32 v23, v23
	v_mul_f32_e32 v22, 0x41800000, v22
	v_add_f32_e32 v23, 1.0, v23
	v_rcp_f32_e32 v23, v23
	s_nop 0
	v_mul_f32_e32 v23, v23, v47
	v_mul_f32_e32 v23, v24, v23
	v_mov_b32_e32 v214, v1
	v_cvt_pk_fp8_f32 v214, v20, v21
	v_mul_f32_e32 v23, 0x41800000, v23
	v_med3_f32 v20, v22, s93, v223
	v_med3_f32 v21, v23, s93, v223
	v_cvt_pk_fp8_f32 v214, v20, v21 op_sel:[0,0,1]
	s_waitcnt vmcnt(2)
	v_permlane32_swap_b32_e32 v42, v44
	v_permlane32_swap_b32_e32 v43, v45
	v_lshlrev_b32_e32 v20, 16, v44
	v_mul_f32_e32 v24, 0xbfb8aa3b, v20
	v_exp_f32_e32 v24, v24
	v_and_b32_e32 v21, 0xffff0000, v44
	v_lshlrev_b32_e32 v22, 16, v45
	v_and_b32_e32 v23, 0xffff0000, v45
	v_add_f32_e32 v24, 1.0, v24
	v_rcp_f32_e32 v24, v24
	s_nop 0
	v_mul_f32_e32 v20, v24, v20
	v_mul_f32_e32 v24, v26, v0
	v_mul_f32_e32 v20, v24, v20
	v_mul_f32_e32 v24, 0xbfb8aa3b, v21
	v_exp_f32_e32 v24, v24
	v_mul_f32_e32 v20, 0x41800000, v20
	v_med3_f32 v20, v20, s93, v223
	v_add_f32_e32 v24, 1.0, v24
	v_rcp_f32_e32 v24, v24
	s_nop 0
	v_mul_f32_e32 v21, v24, v21
	v_mul_f32_e32 v24, v27, v0
	v_mul_f32_e32 v21, v24, v21
	v_mul_f32_e32 v24, 0xbfb8aa3b, v22
	v_exp_f32_e32 v24, v24
	v_mul_f32_e32 v21, 0x41800000, v21
	v_med3_f32 v21, v21, s93, v223
	v_add_f32_e32 v24, 1.0, v24
	v_rcp_f32_e32 v24, v24
	s_nop 0
	v_mul_f32_e32 v22, v24, v22
	v_mul_f32_e32 v24, v28, v0
	v_mul_f32_e32 v22, v24, v22
	v_mul_f32_e32 v24, 0xbfb8aa3b, v23
	v_exp_f32_e32 v24, v24
	v_mul_f32_e32 v22, 0x41800000, v22
	v_add_f32_e32 v24, 1.0, v24
	v_rcp_f32_e32 v24, v24
	s_nop 0
	v_mul_f32_e32 v23, v24, v23
	v_mul_f32_e32 v24, v29, v0
	v_mul_f32_e32 v23, v24, v23
	v_mov_b32_e32 v213, v1
	v_cvt_pk_fp8_f32 v213, v20, v21
	v_mul_f32_e32 v23, 0x41800000, v23
	v_med3_f32 v20, v22, s93, v223
	v_med3_f32 v21, v23, s93, v223
	v_cvt_pk_fp8_f32 v213, v20, v21 op_sel:[0,0,1]
	s_waitcnt vmcnt(2)
; DI float bf2f(unsigned b) { return __uint_as_float(b << 16); }
; template <int DQK, int W1, int DV, int VW, int MODE> ...
;     ...
; #pragma unroll
;   for (int cb = 0; cb < NCB; ++cb)
; #pragma unroll
;     for (int g = 0; g < 4; ++g) {
;       const int dv = 32 * cb + 8 * g + 4 * hi;
;       const u32x2 gg = ggv[cb * 4 + g];
;       float gv[4] = {bf2f(gg[0] & 0xffffu), bf2f(gg[0] >> 16), bf2f(gg[1] & 0xffffu), bf2f(gg[1] >> 16)};
;       float ov[4];
; #pragma unroll
;       for (int j = 0; j < 4; ++j) {
;         const float sg = gv[j] * __builtin_amdgcn_rcpf(1.f + __builtin_amdgcn_exp2f(-LOG2E * gv[j]));
;         ov[j] = o[cb][4 * g + j] * inv * sg;
;       }
;       *(unsigned*)((unsigned char*)yrow + dv) = pk4_fp8(ov[0] * Y_SCALE, ov[1] * Y_SCALE, ov[2] * Y_SCALE, ov[3] * Y_SCALE);
;       __builtin_amdgcn_sched_barrier(0);
;     }
	v_lshlrev_b32_e32 v20, 16, v42
	v_mul_f32_e32 v24, 0xbfb8aa3b, v20
	v_exp_f32_e32 v24, v24
	v_and_b32_e32 v21, 0xffff0000, v42
	v_lshlrev_b32_e32 v22, 16, v43
	v_and_b32_e32 v23, 0xffff0000, v43
	v_add_f32_e32 v24, 1.0, v24
	v_rcp_f32_e32 v24, v24
	s_nop 0
	v_mul_f32_e32 v20, v24, v20
	v_mul_f32_e32 v24, v30, v0
	v_mul_f32_e32 v20, v24, v20
	v_mul_f32_e32 v24, 0xbfb8aa3b, v21
	v_exp_f32_e32 v24, v24
	v_mul_f32_e32 v20, 0x41800000, v20
	v_med3_f32 v20, v20, s93, v223
	v_add_f32_e32 v24, 1.0, v24
	v_rcp_f32_e32 v24, v24
	s_nop 0
	v_mul_f32_e32 v21, v24, v21
	v_mul_f32_e32 v24, v31, v0
	v_mul_f32_e32 v21, v24, v21
	v_mul_f32_e32 v24, 0xbfb8aa3b, v22
	v_exp_f32_e32 v24, v24
	v_mul_f32_e32 v21, 0x41800000, v21
	v_med3_f32 v21, v21, s93, v223
	v_add_f32_e32 v24, 1.0, v24
	v_rcp_f32_e32 v24, v24
	s_nop 0
	v_mul_f32_e32 v22, v24, v22
	v_mul_f32_e32 v24, v32, v0
	v_mul_f32_e32 v22, v24, v22
	v_mul_f32_e32 v24, 0xbfb8aa3b, v23
	v_exp_f32_e32 v24, v24
	v_mul_f32_e32 v22, 0x41800000, v22
	v_add_f32_e32 v24, 1.0, v24
	v_rcp_f32_e32 v24, v24
	s_nop 0
	v_mul_f32_e32 v23, v24, v23
	v_mul_f32_e32 v24, v33, v0
	v_mul_f32_e32 v23, v24, v23
	v_mov_b32_e32 v215, v1
	v_cvt_pk_fp8_f32 v215, v20, v21
	v_mul_f32_e32 v23, 0x41800000, v23
	v_med3_f32 v20, v22, s93, v223
	v_med3_f32 v21, v23, s93, v223
	v_cvt_pk_fp8_f32 v215, v20, v21 op_sel:[0,0,1]
	v_and_b32_e32 v242, 32, v179
	v_lshrrev_b32_e32 v242, 3, v242
	v_lshl_add_u32 v242, v242, 1, v242
	v_mov_b32_e32 v243, 0
	v_lshl_add_u64 v[216:217], v[18:19], 0, v[242:243]
	s_nop 1
	v_permlane32_swap_b32_e32 v212, v213
	v_permlane32_swap_b32_e32 v214, v215
	global_store_dwordx4 v[216:217], v[212:215], off
	s_waitcnt vmcnt(2)
	v_permlane32_swap_b32_e32 v38, v40
	v_permlane32_swap_b32_e32 v39, v41
	v_lshlrev_b32_e32 v20, 16, v40
	v_mul_f32_e32 v24, 0xbfb8aa3b, v20
	v_exp_f32_e32 v24, v24
	v_and_b32_e32 v21, 0xffff0000, v40
	v_mul_f32_e32 v2, v2, v0
	v_lshlrev_b32_e32 v22, 16, v41
	v_add_f32_e32 v24, 1.0, v24
	v_rcp_f32_e32 v24, v24
	v_mul_f32_e32 v3, v3, v0
	v_and_b32_e32 v23, 0xffff0000, v41
	v_mul_f32_e32 v4, v4, v0
	v_mul_f32_e32 v20, v24, v20
	v_mul_f32_e32 v2, v2, v20
	v_mul_f32_e32 v20, 0xbfb8aa3b, v21
	v_exp_f32_e32 v20, v20
	v_mul_f32_e32 v5, v5, v0
	v_mul_f32_e32 v2, 0x41800000, v2
	v_med3_f32 v2, v2, s93, v223
	v_add_f32_e32 v20, 1.0, v20
	v_rcp_f32_e32 v20, v20
	s_nop 0
	v_mul_f32_e32 v20, v20, v21
	v_mul_f32_e32 v3, v3, v20
	v_mul_f32_e32 v20, 0xbfb8aa3b, v22
	v_exp_f32_e32 v20, v20
	v_mul_f32_e32 v3, 0x41800000, v3
	v_med3_f32 v3, v3, s93, v223
	v_add_f32_e32 v20, 1.0, v20
	v_rcp_f32_e32 v20, v20
	s_nop 0
	v_mul_f32_e32 v20, v20, v22
	v_mul_f32_e32 v4, v4, v20
	v_mul_f32_e32 v20, 0xbfb8aa3b, v23
	v_exp_f32_e32 v20, v20
	v_mul_f32_e32 v4, 0x41800000, v4
	v_add_f32_e32 v20, 1.0, v20
	v_rcp_f32_e32 v20, v20
	s_nop 0
	v_mul_f32_e32 v20, v20, v23
	v_mul_f32_e32 v5, v5, v20
	v_mov_b32_e32 v212, v1
	v_cvt_pk_fp8_f32 v212, v2, v3
	v_mul_f32_e32 v5, 0x41800000, v5
	v_med3_f32 v2, v4, s93, v223
	v_med3_f32 v3, v5, s93, v223
	v_cvt_pk_fp8_f32 v212, v2, v3 op_sel:[0,0,1]
	s_waitcnt vmcnt(2)
; DI float bf2f(unsigned b) { return __uint_as_float(b << 16); }
; template <int DQK, int W1, int DV, int VW, int MODE> ...
;     ...
; #pragma unroll
;   for (int cb = 0; cb < NCB; ++cb)
; #pragma unroll
;     for (int g = 0; g < 4; ++g) {
;       const int dv = 32 * cb + 8 * g + 4 * hi;
;       const u32x2 gg = ggv[cb * 4 + g];
;       float gv[4] = {bf2f(gg[0] & 0xffffu), bf2f(gg[0] >> 16), bf2f(gg[1] & 0xffffu), bf2f(gg[1] >> 16)};
;       float ov[4];
; #pragma unroll
;       for (int j = 0; j < 4; ++j) {
;         const float sg = gv[j] * __builtin_amdgcn_rcpf(1.f + __builtin_amdgcn_exp2f(-LOG2E * gv[j]));
;         ov[j] = o[cb][4 * g + j] * inv * sg;
;       }
;       *(unsigned*)((unsigned char*)yrow + dv) = pk4_fp8(ov[0] * Y_SCALE, ov[1] * Y_SCALE, ov[2] * Y_SCALE, ov[3] * Y_SCALE);
;       __builtin_amdgcn_sched_barrier(0);
;     }
	v_lshlrev_b32_e32 v2, 16, v38
	v_mul_f32_e32 v20, 0xbfb8aa3b, v2
	v_exp_f32_e32 v20, v20
	v_and_b32_e32 v3, 0xffff0000, v38
	v_mul_f32_e32 v6, v6, v0
	v_lshlrev_b32_e32 v4, 16, v39
	v_add_f32_e32 v20, 1.0, v20
	v_rcp_f32_e32 v20, v20
	v_and_b32_e32 v5, 0xffff0000, v39
	v_mul_f32_e32 v2, v20, v2
	v_mul_f32_e32 v2, v6, v2
	v_mul_f32_e32 v6, 0xbfb8aa3b, v3
	v_exp_f32_e32 v6, v6
	v_mul_f32_e32 v2, 0x41800000, v2
	v_med3_f32 v2, v2, s93, v223
	v_add_f32_e32 v6, 1.0, v6
	v_rcp_f32_e32 v6, v6
	s_nop 0
	v_mul_f32_e32 v3, v6, v3
	v_mul_f32_e32 v6, v7, v0
	v_mul_f32_e32 v3, v6, v3
	v_mul_f32_e32 v6, 0xbfb8aa3b, v4
	v_exp_f32_e32 v6, v6
	v_mul_f32_e32 v3, 0x41800000, v3
	v_med3_f32 v3, v3, s93, v223
	v_add_f32_e32 v6, 1.0, v6
	v_rcp_f32_e32 v6, v6
	s_nop 0
	v_mul_f32_e32 v4, v6, v4
	v_mul_f32_e32 v6, v8, v0
	v_mul_f32_e32 v4, v6, v4
	v_mul_f32_e32 v6, 0xbfb8aa3b, v5
	v_exp_f32_e32 v6, v6
	v_mul_f32_e32 v4, 0x41800000, v4
	v_add_f32_e32 v6, 1.0, v6
	v_rcp_f32_e32 v6, v6
	s_nop 0
	v_mul_f32_e32 v5, v6, v5
	v_mul_f32_e32 v6, v9, v0
	v_mul_f32_e32 v5, v6, v5
	v_mov_b32_e32 v214, v1
	v_cvt_pk_fp8_f32 v214, v2, v3
	v_mul_f32_e32 v5, 0x41800000, v5
	v_med3_f32 v2, v4, s93, v223
	v_med3_f32 v3, v5, s93, v223
	v_cvt_pk_fp8_f32 v214, v2, v3 op_sel:[0,0,1]
	s_waitcnt vmcnt(1)
	v_permlane32_swap_b32_e32 v34, v36
	v_permlane32_swap_b32_e32 v35, v37
	v_lshlrev_b32_e32 v2, 16, v36
	v_mul_f32_e32 v6, 0xbfb8aa3b, v2
	v_exp_f32_e32 v6, v6
	v_and_b32_e32 v3, 0xffff0000, v36
	v_lshlrev_b32_e32 v4, 16, v37
	v_and_b32_e32 v5, 0xffff0000, v37
	v_add_f32_e32 v6, 1.0, v6
	v_rcp_f32_e32 v6, v6
	s_nop 0
	v_mul_f32_e32 v2, v6, v2
	v_mul_f32_e32 v6, v10, v0
	v_mul_f32_e32 v2, v6, v2
	v_mul_f32_e32 v6, 0xbfb8aa3b, v3
	v_exp_f32_e32 v6, v6
	v_mul_f32_e32 v2, 0x41800000, v2
	v_med3_f32 v2, v2, s93, v223
	v_add_f32_e32 v6, 1.0, v6
	v_rcp_f32_e32 v6, v6
	s_nop 0
	v_mul_f32_e32 v3, v6, v3
	v_mul_f32_e32 v6, v11, v0
	v_mul_f32_e32 v3, v6, v3
	v_mul_f32_e32 v6, 0xbfb8aa3b, v4
	v_exp_f32_e32 v6, v6
	v_mul_f32_e32 v3, 0x41800000, v3
	v_med3_f32 v3, v3, s93, v223
	v_add_f32_e32 v6, 1.0, v6
	v_rcp_f32_e32 v6, v6
	s_nop 0
	v_mul_f32_e32 v4, v6, v4
	v_mul_f32_e32 v6, v12, v0
	v_mul_f32_e32 v4, v6, v4
	v_mul_f32_e32 v6, 0xbfb8aa3b, v5
	v_exp_f32_e32 v6, v6
	v_mul_f32_e32 v4, 0x41800000, v4
	v_add_f32_e32 v6, 1.0, v6
	v_rcp_f32_e32 v6, v6
	s_nop 0
	v_mul_f32_e32 v5, v6, v5
	v_mul_f32_e32 v6, v13, v0
	v_mul_f32_e32 v5, v6, v5
	v_mov_b32_e32 v213, v1
	v_cvt_pk_fp8_f32 v213, v2, v3
	v_mul_f32_e32 v5, 0x41800000, v5
	v_med3_f32 v2, v4, s93, v223
	v_med3_f32 v3, v5, s93, v223
	v_cvt_pk_fp8_f32 v213, v2, v3 op_sel:[0,0,1]
	s_waitcnt vmcnt(1)
	v_lshlrev_b32_e32 v2, 16, v34
	v_mul_f32_e32 v6, 0xbfb8aa3b, v2
	v_exp_f32_e32 v6, v6
	v_and_b32_e32 v3, 0xffff0000, v34
	v_lshlrev_b32_e32 v4, 16, v35
	v_and_b32_e32 v5, 0xffff0000, v35
	v_add_f32_e32 v6, 1.0, v6
	v_rcp_f32_e32 v6, v6
	s_nop 0
	v_mul_f32_e32 v2, v6, v2
	v_mul_f32_e32 v6, v14, v0
	v_mul_f32_e32 v2, v6, v2
	v_mul_f32_e32 v6, 0xbfb8aa3b, v3
	v_exp_f32_e32 v6, v6
	v_mul_f32_e32 v2, 0x41800000, v2
	v_med3_f32 v2, v2, s93, v223
	v_add_f32_e32 v6, 1.0, v6
	v_rcp_f32_e32 v6, v6
	s_nop 0
	v_mul_f32_e32 v3, v6, v3
	v_mul_f32_e32 v6, v15, v0
	v_mul_f32_e32 v3, v6, v3
	v_mul_f32_e32 v6, 0xbfb8aa3b, v4
	v_exp_f32_e32 v6, v6
	v_mul_f32_e32 v3, 0x41800000, v3
	v_med3_f32 v3, v3, s93, v223
	v_add_f32_e32 v6, 1.0, v6
	v_rcp_f32_e32 v6, v6
	s_nop 0
	v_mul_f32_e32 v4, v6, v4
	v_mul_f32_e32 v6, v16, v0
	v_mul_f32_e32 v4, v6, v4
	v_mul_f32_e32 v6, 0xbfb8aa3b, v5
	v_exp_f32_e32 v6, v6
	v_mul_f32_e32 v0, v17, v0
	v_mul_f32_e32 v4, 0x41800000, v4
	v_add_f32_e32 v6, 1.0, v6
	v_rcp_f32_e32 v6, v6
	s_nop 0
	v_mul_f32_e32 v5, v6, v5
	v_mul_f32_e32 v0, v0, v5
	v_mov_b32_e32 v215, v1
	v_cvt_pk_fp8_f32 v215, v2, v3
	v_mul_f32_e32 v0, 0x41800000, v0
	v_med3_f32 v2, v4, s93, v223
	v_med3_f32 v0, v0, s93, v223
	v_cvt_pk_fp8_f32 v215, v2, v0 op_sel:[0,0,1]
	s_nop 1
	v_permlane32_swap_b32_e32 v212, v213
	v_permlane32_swap_b32_e32 v214, v215
	global_store_dwordx4 v[216:217], v[212:215], off offset:32
	s_movk_i32 s20, 0x600
	s_mov_b32 s86, 0x800000
	s_movk_i32 s87, 0x3fff
	v_readlane_b32 s3, v254, 29
